# static priority raise for waves 4-7 now kept across tile epilogue and next tile prologue of each GEMM phase, reset once per phase at the phase-loop header
# speedup vs baseline: 1.0007x; 1.0007x over previous
;     __device__ bool next(int i, Unit& u) const {
;         const long L = (long)i * G + c; if (L >= nwg) return false;
;         int wgid = (int)L; { const int q = nwg / NXCD, r = nwg % NXCD, xcd = wgid % NXCD, off = wgid / NXCD; wgid = (xcd < r ? xcd * (q + 1) : r * (q + 1) + (xcd - r) * q) + off; }
;         const int nig = WGM * nN, gid = wgid / nig, fm = gid * WGM, gsz = (nM - fm) < WGM ? (nM - fm) : WGM;
;         u.pm = fm + ((wgid % nig) % gsz); u.pn = (wgid % nig) / gsz; return true;
; __global__ void __launch_bounds__(512, 2) hymba_fwd(Params p0) {
;     ...
;         Params p = p0;
;         { size_t z = 0; asm volatile("" : "+s"(z)); p.ws = p0.ws + z; p.out = p0.out + z; }
;         switch (ph) {
;         case 0: if (PH_MASK & 1) phase_prep(p, smem); break;
;         case 1: if (PH_MASK & 2) { pg8::Gemm g{(const bf16_t*)(p.ws + WS_XN), (const bf16_t*)(p.ws + WS_WIN), MP, N1P, 2048}; pg8::StaticOrder S; S.init(MP, N1P, gridDim.x, opaque_bid());
;                   Epi1 E{(bf16_t*)(p.ws + WS_U), (float*)(p.ws + WS_SF)}; pg8::gemm_phase((LAS unsigned char*)smem, g, S, E);
;                   convert_in_tail(p, smem, (MP / 256) * (N1P / 256), T_IN, T_IN + T_OUT); } break;
;         case 2: if (PH_MASK & 4) phase_scan(p, smem); break;
;         case 3: if (PH_MASK & 8) phase_mixnorm(p); break;
;         case 4: if (PH_MASK & 16) { pg8::Gemm g{(const bf16_t*)(p.ws + WS_MIX), (const bf16_t*)(p.ws + WS_WOUT), MP, 2048, 4096}; pg8::StaticOrder S; S.init(MP, 2048, gridDim.x, opaque_bid());
;                   Epi2 E{p}; pg8::gemm_phase((LAS unsigned char*)smem, g, S, E);
;                   convert_in_tail(p, smem, (MP / 256) * (2048 / 256), T_IN + T_OUT, T_IN + T_OUT + T_UP); } break;
;         case 5: if (PH_MASK & 32) { pg8::Gemm g{(const bf16_t*)(p.ws + WS_A2), (const bf16_t*)(p.ws + WS_WUP), MP, N3, 2048}; pg8::StaticOrder S; S.init(MP, N3, gridDim.x, opaque_bid());
;                   Epi3 E{(bf16_t*)(p.ws + WS_UP), (const float*)(p.ws + WS_SS2)}; pg8::gemm_phase((LAS unsigned char*)smem, g, S, E);
;                   convert_in_tail(p, smem, (MP / 256) * (N3 / 256), T_IN + T_OUT + T_UP, T_ALL); } break;
;         case 6: if (PH_MASK & 64) phase_act(p); break;
;         case 7: if (PH_MASK & 128) { pg8::Gemm g{(const bf16_t*)(p.ws + WS_ACT), (const bf16_t*)(p.ws + WS_WDOWN), MP, 2048, DFF}; pg8::StaticOrder S; S.init(MP, 2048, gridDim.x, opaque_bid());
.LBB0_5:
	s_setprio 0
	v_readlane_b32 s0, v254, 26
	s_mov_b64 s[4:5], 0
	v_readlane_b32 s2, v254, 28
	v_readlane_b32 s3, v254, 29
	s_add_u32 s82, s2, s4
	s_addc_u32 s83, s3, s5
	v_writelane_b32 v255, s4, 27
	s_lshl_b64 s[2:3], s[4:5], 2
	v_readlane_b32 s1, v254, 27
	v_writelane_b32 v255, s5, 28
	s_add_u32 s0, s0, s2
	v_writelane_b32 v255, s2, 29
	s_addc_u32 s1, s1, s3
	s_mov_b64 s[10:11], 0
	v_writelane_b32 v255, s3, 30
	v_readlane_b32 s2, v254, 1
	v_writelane_b32 v255, s0, 31
	v_readlane_b32 s3, v254, 2
	s_cmp_lt_i32 s2, 4
	v_writelane_b32 v255, s1, 32
	s_mov_b64 s[2:3], 0
	v_writelane_b32 v255, s2, 33
	s_mov_b64 s[0:1], -1
	s_nop 0
	v_writelane_b32 v255, s3, 34
	s_cbranch_scc1 .LBB0_416
	v_readlane_b32 s0, v254, 1
	s_cmp_gt_i32 s0, 5
	v_readlane_b32 s1, v254, 2
	s_cbranch_scc0 .LBB0_48
	s_cmp_gt_i32 s0, 6
	s_cbranch_scc0 .LBB0_49
	s_cmp_eq_u32 s0, 7
	s_mov_b64 s[0:1], -1
	s_cbranch_scc0 .LBB0_54
	v_readlane_b32 s22, v254, 0
	s_waitcnt vmcnt(0)
	v_mov_b32_e32 v12, v151
	s_cmpk_lt_i32 s22, 0x128
	s_cselect_b64 s[0:1], -1, 0
	s_cmpk_gt_i32 s22, 0x127
	v_readfirstlane_b32 s23, v12
	s_cbranch_scc1 .LBB0_11
	s_ashr_i32 s2, s22, 31
	s_lshr_b32 s2, s2, 29
	s_add_i32 s2, s22, s2
	s_ashr_i32 s3, s2, 3
	s_and_b32 s2, s2, -8
	s_sub_i32 s2, s22, s2
	s_cmp_lt_i32 s2, 0
	s_cselect_b32 s4, 33, 32
	s_mul_i32 s2, s2, s4
	s_add_i32 s2, s2, s3
	s_ashr_i32 s3, s2, 31
	s_lshr_b32 s3, s3, 26
	s_add_i32 s3, s2, s3
	s_ashr_i32 s4, s3, 6
	s_lshl_b32 s4, s4, 3
	s_sub_i32 s5, 37, s4
	s_min_u32 s5, s5, 8
	s_andn2_b32 s3, s3, 63
	s_sub_i32 s6, s2, s3
	s_waitcnt lgkmcnt(0)
	v_cvt_f32_ubyte0_e32 v5, s5
	v_cvt_f32_i32_e32 v4, s6
	v_rcp_iflag_f32_e32 v6, v5
	s_ashr_i32 s2, s6, 30
	s_or_b32 s7, s2, 1
	v_mul_f32_e32 v6, v4, v6
	v_trunc_f32_e32 v6, v6
	v_fma_f32 v4, -v6, v5, v4
	v_cvt_i32_f32_e32 v6, v6
	v_cmp_ge_f32_e64 s[2:3], |v4|, v5
	s_and_b64 s[2:3], s[2:3], exec
	s_cselect_b32 s2, s7, 0
	v_readfirstlane_b32 s3, v6
	s_add_i32 s2, s3, s2
	s_sext_i32_i8 s28, s2
	s_mul_i32 s2, s2, s5
	s_sub_i32 s2, s6, s2
	s_sext_i32_i8 s2, s2
	s_add_i32 s29, s4, s2

; #define PG8_STAGE(bufoff, gbase, voff) do { _Pragma("unroll") for (int _i = 0; _i < 2; ++_i) \
;         __builtin_amdgcn_global_load_lds((const unsigned*)((const char*)(gbase) + (voff)[_i]), (LAS unsigned*)(lds + (bufoff) + ldsw + _i * 8192), 16, 0, 0); } while (0)
; #define PG8_LDA(dst, b, h) do { _Pragma("unroll") for (int m = 0; m < 4; ++m) _Pragma("unroll") for (int k = 0; k < 2; ++k) dst[m][k] = *(const LAS bf16x8*)(lds + PG8_SA(b, h) + aoff + m * 2048 + k * 1024); } while (0)
; #define PG8_LDB(dst, b, h) do { _Pragma("unroll") for (int n = 0; n < 2; ++n) _Pragma("unroll") for (int k = 0; k < 2; ++k) dst[n][k] = *(const LAS bf16x8*)(lds + PG8_SB(b, h) + boff + n * 2048 + k * 1024); } while (0)
; #define PG8_MMA(ai, bj, At, Bt) do { __builtin_amdgcn_s_setprio(1); _Pragma("unroll") for (int m = 0; m < 4; ++m) _Pragma("unroll") for (int n = 0; n < 2; ++n) _Pragma("unroll") for (int k = 0; k < 2; ++k) \
;         acc[ai][bj][m][n] = __builtin_amdgcn_mfma_f32_16x16x32_bf16(Bt[n][k], At[m][k], acc[ai][bj][m][n], 0, 0, 0); __builtin_amdgcn_s_setprio(0); } while (0)
; #define PG8_WAIT_V(n) asm volatile("s_waitcnt vmcnt(" #n ")" ::: "memory")
; #define PG8_WAIT_L(n) asm volatile("s_waitcnt lgkmcnt(" #n ")" ::: "memory")
; template <class Epi>
; __device__ __forceinline__ void gemm_phase(LAS unsigned char* lds, const Gemm g, const StaticOrder& S, const Epi& E) {
;     ...
;         for (int t = 0; t < nt; t += 2) {
;             const bool last = (t == nt - 2);
;             const char* a1 = cA + (size_t)(t + 1) * kstep;
;             const char* a2 = last ? nA : cA + (size_t)(t + 2) * kstep; const char* b2 = last ? nB : cB + (size_t)(t + 2) * kstep;
;             const char* a3 = a2 + kstep; const char* b3 = b2 + kstep;
;             PG8_LDB(B0, 0, 0); PG8_SCHED; PG8_LDA(At, 0, 0); PG8_STAGE(PG8_SA(1, 1), a1 + hstep, voffA);
;             PG8_WAIT_L(8); PG8_BAR; PG8_WAIT_L(0); PG8_MMA(0, 0, At, B0); PG8_BAR; PG8_SCHED;
;             PG8_LDB(B1, 0, 1); PG8_STAGE(PG8_SB(0, 0), b2, voffB);
;             PG8_BAR; PG8_WAIT_L(0); PG8_MMA(0, 1, At, B1); PG8_BAR;
;             PG8_LDA(At, 0, 1); PG8_STAGE(PG8_SA(0, 0), a2, voffA);
;             PG8_BAR; PG8_WAIT_L(0); PG8_MMA(1, 0, At, B0); PG8_BAR; PG8_SCHED;
;             PG8_STAGE(PG8_SB(0, 1), b2 + hstep, voffB);
;             PG8_WAIT_V(6); PG8_BAR; PG8_MMA(1, 1, At, B1); PG8_BAR;
.Lprio_skip_23:
.LBB0_23:
	s_add_u32 s6, s16, 0x100
	s_addc_u32 s7, s17, 0
	s_add_i32 s48, 0, 0x10000
	v_add_u32_e32 v178, s48, v147
	ds_read_b128 v[142:145], v178
	ds_read_b128 v[170:173], v178 offset:1024
	ds_read_b128 v[174:177], v178 offset:2048
	ds_read_b128 v[178:181], v178 offset:3072
	s_cmpk_eq_i32 s47, 0x54
	s_cselect_b32 s21, s15, s7
	s_cselect_b32 s20, s14, s6
	s_cselect_b32 s19, s1, s46
	s_cselect_b32 s18, s0, s44
	v_lshl_add_u64 v[226:227], s[16:17], 0, v[138:139]
	s_add_i32 m0, s31, 0xc000
	ds_read_b128 v[182:185], v163
	ds_read_b128 v[186:189], v163 offset:1024
	ds_read_b128 v[190:193], v163 offset:2048
	ds_read_b128 v[194:197], v163 offset:3072
	ds_read_b128 v[198:201], v163 offset:4096
	ds_read_b128 v[214:217], v163 offset:5120
	ds_read_b128 v[218:221], v163 offset:6144
	ds_read_b128 v[222:225], v163 offset:7168
	global_load_lds_dwordx4 v[226:227], off
	v_lshl_add_u64 v[226:227], s[16:17], 0, v[140:141]
	s_add_i32 m0, s31, 0xe000
	s_nop 0
	global_load_lds_dwordx4 v[226:227], off
	s_waitcnt lgkmcnt(8)
	s_barrier
	s_waitcnt lgkmcnt(0)
	s_waitcnt lgkmcnt(0)
	v_mfma_f32_16x16x32_bf16 v[128:131], v[142:145], v[182:185], v[128:131]
	v_mfma_f32_16x16x32_bf16 v[124:127], v[174:177], v[182:185], v[124:127]
	v_mfma_f32_16x16x32_bf16 v[112:115], v[142:145], v[190:193], v[112:115]
	v_mfma_f32_16x16x32_bf16 v[108:111], v[174:177], v[190:193], v[108:111]
	v_mfma_f32_16x16x32_bf16 v[96:99], v[142:145], v[198:201], v[96:99]
	v_mfma_f32_16x16x32_bf16 v[92:95], v[174:177], v[198:201], v[92:95]
	v_mfma_f32_16x16x32_bf16 v[80:83], v[142:145], v[218:221], v[80:83]
	v_mfma_f32_16x16x32_bf16 v[76:79], v[174:177], v[218:221], v[76:79]
	v_mfma_f32_16x16x32_bf16 v[128:131], v[170:173], v[186:189], v[128:131]
	v_mfma_f32_16x16x32_bf16 v[124:127], v[178:181], v[186:189], v[124:127]
	v_mfma_f32_16x16x32_bf16 v[112:115], v[170:173], v[194:197], v[112:115]
	v_mfma_f32_16x16x32_bf16 v[108:111], v[178:181], v[194:197], v[108:111]
	v_mfma_f32_16x16x32_bf16 v[96:99], v[170:173], v[214:217], v[96:99]
	v_mfma_f32_16x16x32_bf16 v[92:95], v[178:181], v[214:217], v[92:95]
	v_mfma_f32_16x16x32_bf16 v[80:83], v[170:173], v[222:225], v[80:83]
	v_mfma_f32_16x16x32_bf16 v[76:79], v[178:181], v[222:225], v[76:79]
	s_barrier
	s_add_i32 s52, 0, 0x14000
	s_add_i32 s16, s48, s30
	v_add_u32_e32 v238, s52, v147
	v_lshl_add_u64 v[242:243], s[18:19], 0, v[148:149]
	s_mov_b32 m0, s16
	ds_read_b128 v[226:229], v238
	ds_read_b128 v[230:233], v238 offset:1024
	ds_read_b128 v[234:237], v238 offset:2048
	ds_read_b128 v[238:241], v238 offset:3072
	global_load_lds_dwordx4 v[242:243], off
	v_lshl_add_u64 v[244:245], s[18:19], 0, v[136:137]
	s_add_i32 m0, s16, 0x2000
	s_nop 0
	global_load_lds_dwordx4 v[244:245], off
	s_barrier
	s_waitcnt lgkmcnt(0)
	s_waitcnt lgkmcnt(0)
	v_mfma_f32_16x16x32_bf16 v[120:123], v[226:229], v[182:185], v[120:123]
	v_mfma_f32_16x16x32_bf16 v[116:119], v[234:237], v[182:185], v[116:119]
	v_mfma_f32_16x16x32_bf16 v[104:107], v[226:229], v[190:193], v[104:107]
	v_mfma_f32_16x16x32_bf16 v[100:103], v[234:237], v[190:193], v[100:103]
	v_mfma_f32_16x16x32_bf16 v[88:91], v[226:229], v[198:201], v[88:91]
	v_mfma_f32_16x16x32_bf16 v[84:87], v[234:237], v[198:201], v[84:87]
	v_mfma_f32_16x16x32_bf16 v[72:75], v[226:229], v[218:221], v[72:75]
	v_mfma_f32_16x16x32_bf16 v[68:71], v[234:237], v[218:221], v[68:71]
	v_mfma_f32_16x16x32_bf16 v[120:123], v[230:233], v[186:189], v[120:123]
	v_mfma_f32_16x16x32_bf16 v[116:119], v[238:241], v[186:189], v[116:119]
	v_mfma_f32_16x16x32_bf16 v[104:107], v[230:233], v[194:197], v[104:107]
	v_mfma_f32_16x16x32_bf16 v[100:103], v[238:241], v[194:197], v[100:103]
	v_mfma_f32_16x16x32_bf16 v[88:91], v[230:233], v[214:217], v[88:91]
	v_mfma_f32_16x16x32_bf16 v[84:87], v[238:241], v[214:217], v[84:87]
	v_mfma_f32_16x16x32_bf16 v[72:75], v[230:233], v[222:225], v[72:75]
	v_mfma_f32_16x16x32_bf16 v[68:71], v[238:241], v[222:225], v[68:71]
	s_mov_b32 m0, s31
	v_lshl_add_u64 v[246:247], s[20:21], 0, v[132:133]
	s_barrier
	ds_read_b128 v[182:185], v163 offset:16384
	ds_read_b128 v[186:189], v163 offset:17408
	ds_read_b128 v[190:193], v163 offset:18432
	ds_read_b128 v[194:197], v163 offset:19456
	ds_read_b128 v[198:201], v163 offset:20480
	ds_read_b128 v[214:217], v163 offset:21504
	ds_read_b128 v[218:221], v163 offset:22528
	ds_read_b128 v[222:225], v163 offset:23552
	global_load_lds_dwordx4 v[246:247], off
	v_lshl_add_u64 v[248:249], s[20:21], 0, v[134:135]
	s_mov_b32 m0, s33
	s_nop 0
	global_load_lds_dwordx4 v[248:249], off
	s_barrier
	s_waitcnt lgkmcnt(0)
	s_waitcnt lgkmcnt(0)
	v_mfma_f32_16x16x32_bf16 v[64:67], v[142:145], v[182:185], v[64:67]
	v_mfma_f32_16x16x32_bf16 v[60:63], v[174:177], v[182:185], v[60:63]
	v_mfma_f32_16x16x32_bf16 v[48:51], v[142:145], v[190:193], v[48:51]
	v_mfma_f32_16x16x32_bf16 v[44:47], v[174:177], v[190:193], v[44:47]
	v_mfma_f32_16x16x32_bf16 v[32:35], v[142:145], v[198:201], v[32:35]
	v_mfma_f32_16x16x32_bf16 v[28:31], v[174:177], v[198:201], v[28:31]
	v_mfma_f32_16x16x32_bf16 v[16:19], v[142:145], v[218:221], v[16:19]
	v_mfma_f32_16x16x32_bf16 v[12:15], v[174:177], v[218:221], v[12:15]
	v_mfma_f32_16x16x32_bf16 v[64:67], v[170:173], v[186:189], v[64:67]
	v_mfma_f32_16x16x32_bf16 v[60:63], v[178:181], v[186:189], v[60:63]
	v_mfma_f32_16x16x32_bf16 v[48:51], v[170:173], v[194:197], v[48:51]
	v_mfma_f32_16x16x32_bf16 v[44:47], v[178:181], v[194:197], v[44:47]
	v_mfma_f32_16x16x32_bf16 v[32:35], v[170:173], v[214:217], v[32:35]
	v_mfma_f32_16x16x32_bf16 v[28:31], v[178:181], v[214:217], v[28:31]
	v_mfma_f32_16x16x32_bf16 v[16:19], v[170:173], v[222:225], v[16:19]
	v_mfma_f32_16x16x32_bf16 v[12:15], v[178:181], v[222:225], v[12:15]
	s_barrier
; #define PG8_STAGE(bufoff, gbase, voff) do { _Pragma("unroll") for (int _i = 0; _i < 2; ++_i) \
;         __builtin_amdgcn_global_load_lds((const unsigned*)((const char*)(gbase) + (voff)[_i]), (LAS unsigned*)(lds + (bufoff) + ldsw + _i * 8192), 16, 0, 0); } while (0)
; #define PG8_LDA(dst, b, h) do { _Pragma("unroll") for (int m = 0; m < 4; ++m) _Pragma("unroll") for (int k = 0; k < 2; ++k) dst[m][k] = *(const LAS bf16x8*)(lds + PG8_SA(b, h) + aoff + m * 2048 + k * 1024); } while (0)
; #define PG8_LDB(dst, b, h) do { _Pragma("unroll") for (int n = 0; n < 2; ++n) _Pragma("unroll") for (int k = 0; k < 2; ++k) dst[n][k] = *(const LAS bf16x8*)(lds + PG8_SB(b, h) + boff + n * 2048 + k * 1024); } while (0)
; #define PG8_MMA(ai, bj, At, Bt) do { __builtin_amdgcn_s_setprio(1); _Pragma("unroll") for (int m = 0; m < 4; ++m) _Pragma("unroll") for (int n = 0; n < 2; ++n) _Pragma("unroll") for (int k = 0; k < 2; ++k) \
;         acc[ai][bj][m][n] = __builtin_amdgcn_mfma_f32_16x16x32_bf16(Bt[n][k], At[m][k], acc[ai][bj][m][n], 0, 0, 0); __builtin_amdgcn_s_setprio(0); } while (0)
; #define PG8_WAIT_V(n) asm volatile("s_waitcnt vmcnt(" #n ")" ::: "memory")
; #define PG8_WAIT_L(n) asm volatile("s_waitcnt lgkmcnt(" #n ")" ::: "memory")
; #define PG8_BAR __builtin_amdgcn_s_barrier()
; #define PG8_SCHED __builtin_amdgcn_sched_barrier(0)
; template <class Epi>
; __device__ __forceinline__ void gemm_phase(LAS unsigned char* lds, const Gemm g, const StaticOrder& S, const Epi& E) {
;     ...
;             PG8_STAGE(PG8_SB(0, 1), b2 + hstep, voffB);
;             PG8_WAIT_V(6); PG8_BAR; PG8_MMA(1, 1, At, B1); PG8_BAR;
;             PG8_LDB(B0, 1, 0); PG8_SCHED; PG8_LDA(At, 1, 0); PG8_STAGE(PG8_SA(0, 1), a2 + hstep, voffA);
;             PG8_WAIT_L(8); PG8_BAR; PG8_WAIT_L(0); PG8_MMA(0, 0, At, B0); PG8_BAR; PG8_SCHED;
;             PG8_LDB(B1, 1, 1); PG8_STAGE(PG8_SB(1, 0), b3, voffB);
;             PG8_BAR; PG8_WAIT_L(0); PG8_MMA(0, 1, At, B1); PG8_BAR;
;             PG8_LDA(At, 1, 1); PG8_STAGE(PG8_SA(1, 0), a3, voffA);
;             PG8_BAR; PG8_WAIT_L(0); PG8_MMA(1, 0, At, B0); PG8_BAR; PG8_SCHED;
	s_add_u32 s16, s18, 0x160000
	s_addc_u32 s17, s19, 0
	s_add_i32 s48, s52, s30
	v_lshl_add_u64 v[142:143], s[16:17], 0, v[148:149]
	s_mov_b32 m0, s48
	s_nop 0
	global_load_lds_dwordx4 v[142:143], off
	v_lshl_add_u64 v[142:143], s[16:17], 0, v[136:137]
	s_add_i32 m0, s48, 0x2000
	s_nop 0
	global_load_lds_dwordx4 v[142:143], off
	s_waitcnt vmcnt(6)
	s_barrier
	v_mfma_f32_16x16x32_bf16 v[56:59], v[226:229], v[182:185], v[56:59]
	v_mfma_f32_16x16x32_bf16 v[52:55], v[234:237], v[182:185], v[52:55]
	v_mfma_f32_16x16x32_bf16 v[40:43], v[226:229], v[190:193], v[40:43]
	v_mfma_f32_16x16x32_bf16 v[36:39], v[234:237], v[190:193], v[36:39]
	v_mfma_f32_16x16x32_bf16 v[24:27], v[226:229], v[198:201], v[24:27]
	v_mfma_f32_16x16x32_bf16 v[20:23], v[234:237], v[198:201], v[20:23]
	v_mfma_f32_16x16x32_bf16 v[8:11], v[226:229], v[218:221], v[8:11]
	v_mfma_f32_16x16x32_bf16 v[4:7], v[234:237], v[218:221], v[4:7]
	v_mfma_f32_16x16x32_bf16 v[56:59], v[230:233], v[186:189], v[56:59]
	v_mfma_f32_16x16x32_bf16 v[52:55], v[238:241], v[186:189], v[52:55]
	v_mfma_f32_16x16x32_bf16 v[40:43], v[230:233], v[194:197], v[40:43]
	v_mfma_f32_16x16x32_bf16 v[36:39], v[238:241], v[194:197], v[36:39]
	v_mfma_f32_16x16x32_bf16 v[24:27], v[230:233], v[214:217], v[24:27]
	v_mfma_f32_16x16x32_bf16 v[20:23], v[238:241], v[214:217], v[20:23]
	v_mfma_f32_16x16x32_bf16 v[8:11], v[230:233], v[222:225], v[8:11]
	v_mfma_f32_16x16x32_bf16 v[4:7], v[238:241], v[222:225], v[4:7]
	s_add_i32 s48, 0, 0x18000
	v_add_u32_e32 v178, s48, v147
	s_barrier
	ds_read_b128 v[142:145], v178
	ds_read_b128 v[170:173], v178 offset:1024
	ds_read_b128 v[174:177], v178 offset:2048
	ds_read_b128 v[178:181], v178 offset:3072
	s_add_u32 s16, s20, 0x160000
	s_addc_u32 s17, s21, 0
	s_mov_b32 m0, s36
	v_lshl_add_u64 v[226:227], s[16:17], 0, v[132:133]
	ds_read_b128 v[182:185], v163 offset:32768
	ds_read_b128 v[186:189], v163 offset:33792
	ds_read_b128 v[190:193], v163 offset:34816
	ds_read_b128 v[194:197], v163 offset:35840
	ds_read_b128 v[198:201], v163 offset:36864
	ds_read_b128 v[214:217], v163 offset:37888
	ds_read_b128 v[218:221], v163 offset:38912
	ds_read_b128 v[222:225], v163 offset:39936
	global_load_lds_dwordx4 v[226:227], off
	v_lshl_add_u64 v[226:227], s[16:17], 0, v[134:135]
	s_mov_b32 m0, s37
	s_nop 0
	global_load_lds_dwordx4 v[226:227], off
	s_waitcnt lgkmcnt(8)
	s_barrier
	s_waitcnt lgkmcnt(0)
	s_waitcnt lgkmcnt(0)
	v_mfma_f32_16x16x32_bf16 v[128:131], v[142:145], v[182:185], v[128:131]
	v_mfma_f32_16x16x32_bf16 v[124:127], v[174:177], v[182:185], v[124:127]
	v_mfma_f32_16x16x32_bf16 v[112:115], v[142:145], v[190:193], v[112:115]
	v_mfma_f32_16x16x32_bf16 v[108:111], v[174:177], v[190:193], v[108:111]
	v_mfma_f32_16x16x32_bf16 v[96:99], v[142:145], v[198:201], v[96:99]
	v_mfma_f32_16x16x32_bf16 v[92:95], v[174:177], v[198:201], v[92:95]
	v_mfma_f32_16x16x32_bf16 v[80:83], v[142:145], v[218:221], v[80:83]
	v_mfma_f32_16x16x32_bf16 v[76:79], v[174:177], v[218:221], v[76:79]
	v_mfma_f32_16x16x32_bf16 v[128:131], v[170:173], v[186:189], v[128:131]
	v_mfma_f32_16x16x32_bf16 v[124:127], v[178:181], v[186:189], v[124:127]
	v_mfma_f32_16x16x32_bf16 v[112:115], v[170:173], v[194:197], v[112:115]
	v_mfma_f32_16x16x32_bf16 v[108:111], v[178:181], v[194:197], v[108:111]
	v_mfma_f32_16x16x32_bf16 v[96:99], v[170:173], v[214:217], v[96:99]
	v_mfma_f32_16x16x32_bf16 v[92:95], v[178:181], v[214:217], v[92:95]
	v_mfma_f32_16x16x32_bf16 v[80:83], v[170:173], v[222:225], v[80:83]
	v_mfma_f32_16x16x32_bf16 v[76:79], v[178:181], v[222:225], v[76:79]
	s_barrier
	s_add_i32 s20, 0, 0x1c000
	s_add_i32 s16, s48, s30
	v_add_u32_e32 v238, s20, v147
	v_lshl_add_u64 v[242:243], v[242:243], 0, s[34:35]
	s_mov_b32 m0, s16
	ds_read_b128 v[226:229], v238
	ds_read_b128 v[230:233], v238 offset:1024
	ds_read_b128 v[234:237], v238 offset:2048
	ds_read_b128 v[238:241], v238 offset:3072
	global_load_lds_dwordx4 v[242:243], off
	v_lshl_add_u64 v[242:243], v[244:245], 0, s[34:35]
	s_add_i32 m0, s16, 0x2000
	s_nop 0
	global_load_lds_dwordx4 v[242:243], off
	s_barrier
	s_waitcnt lgkmcnt(0)
	s_waitcnt lgkmcnt(0)
	v_mfma_f32_16x16x32_bf16 v[120:123], v[226:229], v[182:185], v[120:123]
	v_mfma_f32_16x16x32_bf16 v[116:119], v[234:237], v[182:185], v[116:119]
	v_mfma_f32_16x16x32_bf16 v[104:107], v[226:229], v[190:193], v[104:107]
	v_mfma_f32_16x16x32_bf16 v[100:103], v[234:237], v[190:193], v[100:103]
	v_mfma_f32_16x16x32_bf16 v[88:91], v[226:229], v[198:201], v[88:91]
	v_mfma_f32_16x16x32_bf16 v[84:87], v[234:237], v[198:201], v[84:87]
	v_mfma_f32_16x16x32_bf16 v[72:75], v[226:229], v[218:221], v[72:75]
	v_mfma_f32_16x16x32_bf16 v[68:71], v[234:237], v[218:221], v[68:71]
	v_mfma_f32_16x16x32_bf16 v[120:123], v[230:233], v[186:189], v[120:123]
	v_mfma_f32_16x16x32_bf16 v[116:119], v[238:241], v[186:189], v[116:119]
	v_mfma_f32_16x16x32_bf16 v[104:107], v[230:233], v[194:197], v[104:107]
	v_mfma_f32_16x16x32_bf16 v[100:103], v[238:241], v[194:197], v[100:103]
	v_mfma_f32_16x16x32_bf16 v[88:91], v[230:233], v[214:217], v[88:91]
	v_mfma_f32_16x16x32_bf16 v[84:87], v[238:241], v[214:217], v[84:87]
	v_mfma_f32_16x16x32_bf16 v[72:75], v[230:233], v[222:225], v[72:75]
	v_mfma_f32_16x16x32_bf16 v[68:71], v[238:241], v[222:225], v[68:71]
	s_mov_b32 m0, s38
	v_lshl_add_u64 v[242:243], v[246:247], 0, s[34:35]
	s_barrier
	ds_read_b128 v[182:185], v163 offset:49152
	ds_read_b128 v[186:189], v163 offset:50176
	ds_read_b128 v[190:193], v163 offset:51200
	ds_read_b128 v[194:197], v163 offset:52224
	ds_read_b128 v[198:201], v163 offset:53248
	ds_read_b128 v[214:217], v163 offset:54272
	ds_read_b128 v[218:221], v163 offset:55296
	ds_read_b128 v[222:225], v163 offset:56320
	global_load_lds_dwordx4 v[242:243], off
	v_lshl_add_u64 v[242:243], v[248:249], 0, s[34:35]
	s_mov_b32 m0, s39
	s_nop 0
	global_load_lds_dwordx4 v[242:243], off
	s_barrier
; #define PG8_LDA(dst, b, h) do { _Pragma("unroll") for (int m = 0; m < 4; ++m) _Pragma("unroll") for (int k = 0; k < 2; ++k) dst[m][k] = *(const LAS bf16x8*)(lds + PG8_SA(b, h) + aoff + m * 2048 + k * 1024); } while (0)
; template <class Epi>
; __device__ __forceinline__ void gemm_phase(LAS unsigned char* lds, const Gemm g, const StaticOrder& S, const Epi& E) {
;     ...
;             PG8_WAIT_V(6); PG8_BAR; PG8_MMA(1, 1, At, B1); PG8_BAR;
;             PG8_LDB(B0, 1, 0); PG8_SCHED; PG8_LDA(At, 1, 0); PG8_STAGE(PG8_SA(0, 1), a2 + hstep, voffA);
;             PG8_WAIT_L(8); PG8_BAR; PG8_WAIT_L(0); PG8_MMA(0, 0, At, B0); PG8_BAR; PG8_SCHED;
;             PG8_LDB(B1, 1, 1); PG8_STAGE(PG8_SB(1, 0), b3, voffB);
;             PG8_BAR; PG8_WAIT_L(0); PG8_MMA(0, 1, At, B1); PG8_BAR;
;             PG8_LDA(At, 1, 1); PG8_STAGE(PG8_SA(1, 0), a3, voffA);
;             PG8_BAR; PG8_WAIT_L(0); PG8_MMA(1, 0, At, B0); PG8_BAR; PG8_SCHED;
;             PG8_STAGE(PG8_SB(1, 1), b3 + hstep, voffB);
;             PG8_WAIT_V(6); PG8_BAR; PG8_MMA(1, 1, At, B1); PG8_BAR;
;     __device__ __forceinline__ void operator()(const AccT& acc, const pg8::Unit& u, int wr, int wc, int fr, int fq) const {
;         const int row0 = u.pm * 256 + wr * 64 + fr, col0 = u.pn * 256 + wc * 32 + 8 * fq;
; #pragma unroll
;         for (int ai = 0; ai < 2; ++ai)
; #pragma unroll
;             for (int m = 0; m < 4; ++m) {
;                 const int row = row0 + ai * 128 + m * 16;
;                 if (row < NOUTROWS) {
;                     float ss = 0.f;
; #pragma unroll
;                     for (int bj = 0; bj < 2; ++bj) {
;                         const f32x4 v0 = acc[ai][bj][m][0] + __builtin_nontemporal_load((const f32x4*)(H1 + (size_t)row * DM + col0 + bj * 128));
;                         const f32x4 v1 = acc[ai][bj][m][1] + __builtin_nontemporal_load((const f32x4*)(H1 + (size_t)row * DM + col0 + bj * 128 + 4));
;                         *(f32x4*)(out + (size_t)row * DM + col0 + bj * 128) = v0; *(f32x4*)(out + (size_t)row * DM + col0 + bj * 128 + 4) = v1;
;                         ss += v0[0] * v0[0] + v0[1] * v0[1] + v0[2] * v0[2] + v0[3] * v0[3] + v1[0] * v1[0] + v1[1] * v1[1] + v1[2] * v1[2] + v1[3] * v1[3];
;                     }
;                     ss += __shfl_xor(ss, 16); ss += __shfl_xor(ss, 32);
;                     if (fq == 0) atomicAdd(SS3 + row, ss);
	s_waitcnt lgkmcnt(0)
	s_waitcnt lgkmcnt(0)
	v_mfma_f32_16x16x32_bf16 v[64:67], v[142:145], v[182:185], v[64:67]
	v_mfma_f32_16x16x32_bf16 v[60:63], v[174:177], v[182:185], v[60:63]
	v_mfma_f32_16x16x32_bf16 v[48:51], v[142:145], v[190:193], v[48:51]
	v_mfma_f32_16x16x32_bf16 v[44:47], v[174:177], v[190:193], v[44:47]
	v_mfma_f32_16x16x32_bf16 v[32:35], v[142:145], v[198:201], v[32:35]
	v_mfma_f32_16x16x32_bf16 v[28:31], v[174:177], v[198:201], v[28:31]
	v_mfma_f32_16x16x32_bf16 v[16:19], v[142:145], v[218:221], v[16:19]
	v_mfma_f32_16x16x32_bf16 v[12:15], v[174:177], v[218:221], v[12:15]
	v_mfma_f32_16x16x32_bf16 v[64:67], v[170:173], v[186:189], v[64:67]
	v_mfma_f32_16x16x32_bf16 v[60:63], v[178:181], v[186:189], v[60:63]
	v_mfma_f32_16x16x32_bf16 v[48:51], v[170:173], v[194:197], v[48:51]
	v_mfma_f32_16x16x32_bf16 v[44:47], v[178:181], v[194:197], v[44:47]
	v_mfma_f32_16x16x32_bf16 v[32:35], v[170:173], v[214:217], v[32:35]
	v_mfma_f32_16x16x32_bf16 v[28:31], v[178:181], v[214:217], v[28:31]
	v_mfma_f32_16x16x32_bf16 v[16:19], v[170:173], v[222:225], v[16:19]
	v_mfma_f32_16x16x32_bf16 v[12:15], v[178:181], v[222:225], v[12:15]
	s_barrier
	s_add_u32 s16, s18, 0x160080
	s_addc_u32 s17, s19, 0
	s_add_i32 s18, s20, s30
	v_lshl_add_u64 v[142:143], s[16:17], 0, v[148:149]
	s_mov_b32 m0, s18
	s_nop 0
	global_load_lds_dwordx4 v[142:143], off
	v_lshl_add_u64 v[142:143], s[16:17], 0, v[136:137]
	s_add_i32 m0, s18, 0x2000
	s_nop 0
	global_load_lds_dwordx4 v[142:143], off
	s_waitcnt vmcnt(6)
	s_barrier
	v_mfma_f32_16x16x32_bf16 v[56:59], v[226:229], v[182:185], v[56:59]
	v_mfma_f32_16x16x32_bf16 v[52:55], v[234:237], v[182:185], v[52:55]
	v_mfma_f32_16x16x32_bf16 v[40:43], v[226:229], v[190:193], v[40:43]
	v_mfma_f32_16x16x32_bf16 v[36:39], v[234:237], v[190:193], v[36:39]
	v_mfma_f32_16x16x32_bf16 v[24:27], v[226:229], v[198:201], v[24:27]
	v_mfma_f32_16x16x32_bf16 v[20:23], v[234:237], v[198:201], v[20:23]
	v_mfma_f32_16x16x32_bf16 v[8:11], v[226:229], v[218:221], v[8:11]
	v_mfma_f32_16x16x32_bf16 v[4:7], v[234:237], v[218:221], v[4:7]
	v_mfma_f32_16x16x32_bf16 v[56:59], v[230:233], v[186:189], v[56:59]
	v_mfma_f32_16x16x32_bf16 v[52:55], v[238:241], v[186:189], v[52:55]
	v_mfma_f32_16x16x32_bf16 v[40:43], v[230:233], v[194:197], v[40:43]
	v_mfma_f32_16x16x32_bf16 v[36:39], v[238:241], v[194:197], v[36:39]
	v_mfma_f32_16x16x32_bf16 v[24:27], v[230:233], v[214:217], v[24:27]
	v_mfma_f32_16x16x32_bf16 v[20:23], v[238:241], v[214:217], v[20:23]
	v_mfma_f32_16x16x32_bf16 v[8:11], v[230:233], v[222:225], v[8:11]
	v_mfma_f32_16x16x32_bf16 v[4:7], v[238:241], v[222:225], v[4:7]
	s_add_i32 s47, s47, 2
	s_add_u32 s44, s44, 0x100
	s_addc_u32 s46, s46, 0
	s_cmpk_gt_u32 s47, 0x55
	s_mov_b64 s[16:17], s[6:7]
	s_barrier
	s_cbranch_scc0 .LBB0_23
	s_cmp_eq_u32 s40, 2
	s_cbranch_scc1 .Lp7_partial_epilogue
	s_movk_i32 s6, 0x2400
	v_lshl_or_b32 v142, s42, 8, v153
	v_lshl_add_u32 v144, s43, 8, v146
	v_ashrrev_i32_e32 v143, 31, v142
	v_cmp_gt_i32_e32 vcc, s6, v144
	v_lshlrev_b64 v[142:143], 2, v[142:143]
	s_and_saveexec_b64 s[6:7], vcc
	s_cbranch_execz .LBB0_27
	v_ashrrev_i32_e32 v145, 31, v144
	v_lshlrev_b64 v[178:179], 13, v[144:145]
	v_lshl_add_u64 v[170:171], s[2:3], 0, v[178:179]
	v_lshl_add_u64 v[180:181], v[170:171], 0, v[142:143]
	global_load_dwordx4 v[170:173], v[180:181], off nt
	global_load_dwordx4 v[174:177], v[180:181], off offset:16 nt
	v_readlane_b32 s16, v255, 31
	v_readlane_b32 s17, v255, 32
	s_waitcnt vmcnt(0)
	v_pk_add_f32 v[130:131], v[130:131], v[172:173]
	v_lshl_add_u64 v[178:179], s[16:17], 0, v[178:179]
	v_lshl_add_u64 v[178:179], v[178:179], 0, v[142:143]
	v_pk_add_f32 v[128:129], v[128:129], v[170:171]
	v_pk_add_f32 v[126:127], v[126:127], v[176:177]
	v_pk_add_f32 v[124:125], v[124:125], v[174:175]
	global_store_dwordx4 v[178:179], v[128:131], off
	global_store_dwordx4 v[178:179], v[124:127], off offset:16
	global_load_dwordx4 v[170:173], v[180:181], off offset:512 nt
	global_load_dwordx4 v[174:177], v[180:181], off offset:528 nt
	v_mul_f32_e32 v129, v129, v129
	v_fmac_f32_e32 v129, v128, v128
	v_fmac_f32_e32 v129, v130, v130
	v_fmac_f32_e32 v129, v131, v131
	v_fmac_f32_e32 v129, v124, v124
	v_fmac_f32_e32 v129, v125, v125
	v_and_b32_e32 v181, 64, v206
	v_fmac_f32_e32 v129, v126, v126
	v_xor_b32_e32 v180, 16, v206
	v_add_u32_e32 v181, 64, v181
	v_fmac_f32_e32 v129, v127, v127
	v_cmp_lt_i32_e32 vcc, v180, v181
	s_waitcnt vmcnt(0)
	v_pk_add_f32 v[120:121], v[120:121], v[170:171]
	v_pk_add_f32 v[124:125], v[116:117], v[174:175]
	v_mul_f32_e32 v116, v121, v121
	v_pk_add_f32 v[122:123], v[122:123], v[172:173]
	v_fmac_f32_e32 v116, v120, v120
	v_fmac_f32_e32 v116, v122, v122
	v_fmac_f32_e32 v116, v123, v123
	v_fmac_f32_e32 v116, v124, v124
	v_pk_add_f32 v[126:127], v[118:119], v[176:177]
	v_fmac_f32_e32 v116, v125, v125
	v_fmac_f32_e32 v116, v126, v126
	v_cndmask_b32_e32 v180, v206, v180, vcc
	v_fmac_f32_e32 v116, v127, v127
	v_lshlrev_b32_e32 v180, 2, v180
	v_add_f32_e32 v116, v129, v116
	ds_bpermute_b32 v117, v180, v116
	v_xor_b32_e32 v118, 32, v206
	v_cmp_lt_i32_e32 vcc, v118, v181
	global_store_dwordx4 v[178:179], v[120:123], off offset:512
	global_store_dwordx4 v[178:179], v[124:127], off offset:528
	v_cndmask_b32_e32 v118, v206, v118, vcc
	s_waitcnt lgkmcnt(0)
	v_add_f32_e32 v116, v116, v117
	v_lshlrev_b32_e32 v117, 2, v118
	ds_bpermute_b32 v117, v117, v116
	s_and_b64 exec, exec, s[8:9]
	s_cbranch_execz .LBB0_27
	v_lshl_add_u64 v[118:119], v[144:145], 2, s[12:13]
	s_waitcnt lgkmcnt(0)
	v_add_f32_e32 v116, v116, v117
	global_atomic_add_f32 v[118:119], v116, off

; #define PG8_STAGE(bufoff, gbase, voff) do { _Pragma("unroll") for (int _i = 0; _i < 2; ++_i) \
;         __builtin_amdgcn_global_load_lds((const unsigned*)((const char*)(gbase) + (voff)[_i]), (LAS unsigned*)(lds + (bufoff) + ldsw + _i * 8192), 16, 0, 0); } while (0)
; #define PG8_LDA(dst, b, h) do { _Pragma("unroll") for (int m = 0; m < 4; ++m) _Pragma("unroll") for (int k = 0; k < 2; ++k) dst[m][k] = *(const LAS bf16x8*)(lds + PG8_SA(b, h) + aoff + m * 2048 + k * 1024); } while (0)
; #define PG8_LDB(dst, b, h) do { _Pragma("unroll") for (int n = 0; n < 2; ++n) _Pragma("unroll") for (int k = 0; k < 2; ++k) dst[n][k] = *(const LAS bf16x8*)(lds + PG8_SB(b, h) + boff + n * 2048 + k * 1024); } while (0)
; #define PG8_MMA(ai, bj, At, Bt) do { __builtin_amdgcn_s_setprio(1); _Pragma("unroll") for (int m = 0; m < 4; ++m) _Pragma("unroll") for (int n = 0; n < 2; ++n) _Pragma("unroll") for (int k = 0; k < 2; ++k) \
;         acc[ai][bj][m][n] = __builtin_amdgcn_mfma_f32_16x16x32_bf16(Bt[n][k], At[m][k], acc[ai][bj][m][n], 0, 0, 0); __builtin_amdgcn_s_setprio(0); } while (0)
; #define PG8_WAIT_V(n) asm volatile("s_waitcnt vmcnt(" #n ")" ::: "memory")
; #define PG8_WAIT_L(n) asm volatile("s_waitcnt lgkmcnt(" #n ")" ::: "memory")
; template <class Epi>
; __device__ __forceinline__ void gemm_phase(LAS unsigned char* lds, const Gemm g, const StaticOrder& S, const Epi& E) {
;     ...
;         for (int t = 0; t < nt; t += 2) {
;             const bool last = (t == nt - 2);
;             const char* a1 = cA + (size_t)(t + 1) * kstep;
;             const char* a2 = last ? nA : cA + (size_t)(t + 2) * kstep; const char* b2 = last ? nB : cB + (size_t)(t + 2) * kstep;
;             const char* a3 = a2 + kstep; const char* b3 = b2 + kstep;
;             PG8_LDB(B0, 0, 0); PG8_SCHED; PG8_LDA(At, 0, 0); PG8_STAGE(PG8_SA(1, 1), a1 + hstep, voffA);
;             PG8_WAIT_L(8); PG8_BAR; PG8_WAIT_L(0); PG8_MMA(0, 0, At, B0); PG8_BAR; PG8_SCHED;
;             PG8_LDB(B1, 0, 1); PG8_STAGE(PG8_SB(0, 0), b2, voffB);
;             PG8_BAR; PG8_WAIT_L(0); PG8_MMA(0, 1, At, B1); PG8_BAR;
;             PG8_LDA(At, 0, 1); PG8_STAGE(PG8_SA(0, 0), a2, voffA);
;             PG8_BAR; PG8_WAIT_L(0); PG8_MMA(1, 0, At, B0); PG8_BAR; PG8_SCHED;
;             PG8_STAGE(PG8_SB(0, 1), b2 + hstep, voffB);
;             PG8_WAIT_V(6); PG8_BAR; PG8_MMA(1, 1, At, B1); PG8_BAR;
.Lprio_skip_98:
.LBB0_98:
	s_add_u32 s22, s20, 0xfff80080
	s_addc_u32 s23, s21, -1
	s_add_i32 s48, 0, 0x10000
	v_add_u32_e32 v146, s48, v163
	ds_read_b128 v[142:145], v146
	ds_read_b128 v[174:177], v146 offset:1024
	ds_read_b128 v[178:181], v146 offset:2048
	ds_read_b128 v[182:185], v146 offset:3072
	s_cmp_eq_u32 s47, 28
	s_cselect_b32 s25, s13, s23
	s_cselect_b32 s24, s42, s22
	s_cselect_b32 s23, s9, s46
	s_cselect_b32 s22, s43, s44
	v_lshl_add_u64 v[146:147], s[20:21], 0, v[138:139]
	s_add_i32 m0, s19, 0xc000
	ds_read_b128 v[186:189], v173
	ds_read_b128 v[190:193], v173 offset:1024
	ds_read_b128 v[194:197], v173 offset:2048
	ds_read_b128 v[198:201], v173 offset:3072
	ds_read_b128 v[214:217], v173 offset:4096
	ds_read_b128 v[218:221], v173 offset:5120
	ds_read_b128 v[222:225], v173 offset:6144
	ds_read_b128 v[226:229], v173 offset:7168
	global_load_lds_dwordx4 v[146:147], off
	v_lshl_add_u64 v[146:147], s[20:21], 0, v[140:141]
	s_add_i32 m0, s19, 0xe000
	s_nop 0
	global_load_lds_dwordx4 v[146:147], off
	s_waitcnt lgkmcnt(8)
	s_barrier
	s_waitcnt lgkmcnt(0)
	s_waitcnt lgkmcnt(0)
	v_mfma_f32_16x16x32_bf16 v[128:131], v[142:145], v[186:189], v[128:131]
	v_mfma_f32_16x16x32_bf16 v[124:127], v[178:181], v[186:189], v[124:127]
	v_mfma_f32_16x16x32_bf16 v[112:115], v[142:145], v[194:197], v[112:115]
	v_mfma_f32_16x16x32_bf16 v[108:111], v[178:181], v[194:197], v[108:111]
	v_mfma_f32_16x16x32_bf16 v[96:99], v[142:145], v[214:217], v[96:99]
	v_mfma_f32_16x16x32_bf16 v[92:95], v[178:181], v[214:217], v[92:95]
	v_mfma_f32_16x16x32_bf16 v[80:83], v[142:145], v[222:225], v[80:83]
	v_mfma_f32_16x16x32_bf16 v[76:79], v[178:181], v[222:225], v[76:79]
	v_mfma_f32_16x16x32_bf16 v[128:131], v[174:177], v[190:193], v[128:131]
	v_mfma_f32_16x16x32_bf16 v[124:127], v[182:185], v[190:193], v[124:127]
	v_mfma_f32_16x16x32_bf16 v[112:115], v[174:177], v[198:201], v[112:115]
	v_mfma_f32_16x16x32_bf16 v[108:111], v[182:185], v[198:201], v[108:111]
	v_mfma_f32_16x16x32_bf16 v[96:99], v[174:177], v[218:221], v[96:99]
	v_mfma_f32_16x16x32_bf16 v[92:95], v[182:185], v[218:221], v[92:95]
	v_mfma_f32_16x16x32_bf16 v[80:83], v[174:177], v[226:229], v[80:83]
	v_mfma_f32_16x16x32_bf16 v[76:79], v[182:185], v[226:229], v[76:79]
	s_barrier
	s_add_i32 s52, 0, 0x14000
	v_add_u32_e32 v146, s52, v163
	s_add_i32 s48, s48, s31
	ds_read_b128 v[230:233], v146
	ds_read_b128 v[234:237], v146 offset:1024
	ds_read_b128 v[238:241], v146 offset:2048
	ds_read_b128 v[242:245], v146 offset:3072
	v_lshl_add_u64 v[146:147], s[22:23], 0, v[148:149]
	s_mov_b32 m0, s48
	v_lshl_add_u64 v[170:171], s[22:23], 0, v[136:137]
	global_load_lds_dwordx4 v[146:147], off
	s_add_i32 m0, s48, 0x2000
	s_nop 0
	global_load_lds_dwordx4 v[170:171], off
	s_barrier
	s_waitcnt lgkmcnt(0)
	s_waitcnt lgkmcnt(0)
	v_mfma_f32_16x16x32_bf16 v[120:123], v[230:233], v[186:189], v[120:123]
	v_mfma_f32_16x16x32_bf16 v[116:119], v[238:241], v[186:189], v[116:119]
	v_mfma_f32_16x16x32_bf16 v[104:107], v[230:233], v[194:197], v[104:107]
	v_mfma_f32_16x16x32_bf16 v[100:103], v[238:241], v[194:197], v[100:103]
	v_mfma_f32_16x16x32_bf16 v[88:91], v[230:233], v[214:217], v[88:91]
	v_mfma_f32_16x16x32_bf16 v[84:87], v[238:241], v[214:217], v[84:87]
	v_mfma_f32_16x16x32_bf16 v[72:75], v[230:233], v[222:225], v[72:75]
	v_mfma_f32_16x16x32_bf16 v[68:71], v[238:241], v[222:225], v[68:71]
	v_mfma_f32_16x16x32_bf16 v[120:123], v[234:237], v[190:193], v[120:123]
	v_mfma_f32_16x16x32_bf16 v[116:119], v[242:245], v[190:193], v[116:119]
	v_mfma_f32_16x16x32_bf16 v[104:107], v[234:237], v[198:201], v[104:107]
	v_mfma_f32_16x16x32_bf16 v[100:103], v[242:245], v[198:201], v[100:103]
	v_mfma_f32_16x16x32_bf16 v[88:91], v[234:237], v[218:221], v[88:91]
	v_mfma_f32_16x16x32_bf16 v[84:87], v[242:245], v[218:221], v[84:87]
	v_mfma_f32_16x16x32_bf16 v[72:75], v[234:237], v[226:229], v[72:75]
	v_mfma_f32_16x16x32_bf16 v[68:71], v[242:245], v[226:229], v[68:71]
	s_mov_b32 m0, s19
	v_lshl_add_u64 v[246:247], s[24:25], 0, v[132:133]
	s_barrier
	ds_read_b128 v[186:189], v173 offset:16384
	ds_read_b128 v[190:193], v173 offset:17408
	ds_read_b128 v[194:197], v173 offset:18432
	ds_read_b128 v[198:201], v173 offset:19456
	ds_read_b128 v[214:217], v173 offset:20480
	ds_read_b128 v[218:221], v173 offset:21504
	ds_read_b128 v[222:225], v173 offset:22528
	ds_read_b128 v[226:229], v173 offset:23552
	global_load_lds_dwordx4 v[246:247], off
	v_lshl_add_u64 v[248:249], s[24:25], 0, v[134:135]
	s_mov_b32 m0, s33
	s_nop 0
	global_load_lds_dwordx4 v[248:249], off
	s_barrier
	s_waitcnt lgkmcnt(0)
	s_waitcnt lgkmcnt(0)
	v_mfma_f32_16x16x32_bf16 v[64:67], v[142:145], v[186:189], v[64:67]
	v_mfma_f32_16x16x32_bf16 v[60:63], v[178:181], v[186:189], v[60:63]
	v_mfma_f32_16x16x32_bf16 v[48:51], v[142:145], v[194:197], v[48:51]
	v_mfma_f32_16x16x32_bf16 v[44:47], v[178:181], v[194:197], v[44:47]
	v_mfma_f32_16x16x32_bf16 v[32:35], v[142:145], v[214:217], v[32:35]
	v_mfma_f32_16x16x32_bf16 v[28:31], v[178:181], v[214:217], v[28:31]
	v_mfma_f32_16x16x32_bf16 v[16:19], v[142:145], v[222:225], v[16:19]
	v_mfma_f32_16x16x32_bf16 v[12:15], v[178:181], v[222:225], v[12:15]
	v_mfma_f32_16x16x32_bf16 v[64:67], v[174:177], v[190:193], v[64:67]
	v_mfma_f32_16x16x32_bf16 v[60:63], v[182:185], v[190:193], v[60:63]
	v_mfma_f32_16x16x32_bf16 v[48:51], v[174:177], v[198:201], v[48:51]
	v_mfma_f32_16x16x32_bf16 v[44:47], v[182:185], v[198:201], v[44:47]
	v_mfma_f32_16x16x32_bf16 v[32:35], v[174:177], v[218:221], v[32:35]
	v_mfma_f32_16x16x32_bf16 v[28:31], v[182:185], v[218:221], v[28:31]
	v_mfma_f32_16x16x32_bf16 v[16:19], v[174:177], v[226:229], v[16:19]
	v_mfma_f32_16x16x32_bf16 v[12:15], v[182:185], v[226:229], v[12:15]
	s_barrier
; #define PG8_STAGE(bufoff, gbase, voff) do { _Pragma("unroll") for (int _i = 0; _i < 2; ++_i) \
;         __builtin_amdgcn_global_load_lds((const unsigned*)((const char*)(gbase) + (voff)[_i]), (LAS unsigned*)(lds + (bufoff) + ldsw + _i * 8192), 16, 0, 0); } while (0)
; #define PG8_LDA(dst, b, h) do { _Pragma("unroll") for (int m = 0; m < 4; ++m) _Pragma("unroll") for (int k = 0; k < 2; ++k) dst[m][k] = *(const LAS bf16x8*)(lds + PG8_SA(b, h) + aoff + m * 2048 + k * 1024); } while (0)
; #define PG8_LDB(dst, b, h) do { _Pragma("unroll") for (int n = 0; n < 2; ++n) _Pragma("unroll") for (int k = 0; k < 2; ++k) dst[n][k] = *(const LAS bf16x8*)(lds + PG8_SB(b, h) + boff + n * 2048 + k * 1024); } while (0)
; #define PG8_MMA(ai, bj, At, Bt) do { __builtin_amdgcn_s_setprio(1); _Pragma("unroll") for (int m = 0; m < 4; ++m) _Pragma("unroll") for (int n = 0; n < 2; ++n) _Pragma("unroll") for (int k = 0; k < 2; ++k) \
;         acc[ai][bj][m][n] = __builtin_amdgcn_mfma_f32_16x16x32_bf16(Bt[n][k], At[m][k], acc[ai][bj][m][n], 0, 0, 0); __builtin_amdgcn_s_setprio(0); } while (0)
; #define PG8_WAIT_V(n) asm volatile("s_waitcnt vmcnt(" #n ")" ::: "memory")
; #define PG8_WAIT_L(n) asm volatile("s_waitcnt lgkmcnt(" #n ")" ::: "memory")
; #define PG8_BAR __builtin_amdgcn_s_barrier()
; #define PG8_SCHED __builtin_amdgcn_sched_barrier(0)
; template <class Epi>
; __device__ __forceinline__ void gemm_phase(LAS unsigned char* lds, const Gemm g, const StaticOrder& S, const Epi& E) {
;     ...
;             PG8_STAGE(PG8_SB(0, 1), b2 + hstep, voffB);
;             PG8_WAIT_V(6); PG8_BAR; PG8_MMA(1, 1, At, B1); PG8_BAR;
;             PG8_LDB(B0, 1, 0); PG8_SCHED; PG8_LDA(At, 1, 0); PG8_STAGE(PG8_SA(0, 1), a2 + hstep, voffA);
;             PG8_WAIT_L(8); PG8_BAR; PG8_WAIT_L(0); PG8_MMA(0, 0, At, B0); PG8_BAR; PG8_SCHED;
;             PG8_LDB(B1, 1, 1); PG8_STAGE(PG8_SB(1, 0), b3, voffB);
;             PG8_BAR; PG8_WAIT_L(0); PG8_MMA(0, 1, At, B1); PG8_BAR;
;             PG8_LDA(At, 1, 1); PG8_STAGE(PG8_SA(1, 0), a3, voffA);
;             PG8_BAR; PG8_WAIT_L(0); PG8_MMA(1, 0, At, B0); PG8_BAR; PG8_SCHED;
	s_add_u32 s72, s22, 0x80000
	s_addc_u32 s73, s23, 0
	s_add_i32 s48, s52, s31
	v_lshl_add_u64 v[142:143], s[72:73], 0, v[148:149]
	s_mov_b32 m0, s48
	s_nop 0
	global_load_lds_dwordx4 v[142:143], off
	v_lshl_add_u64 v[142:143], s[72:73], 0, v[136:137]
	s_add_i32 m0, s48, 0x2000
	s_nop 0
	global_load_lds_dwordx4 v[142:143], off
	s_waitcnt vmcnt(6)
	s_barrier
	v_mfma_f32_16x16x32_bf16 v[56:59], v[230:233], v[186:189], v[56:59]
	v_mfma_f32_16x16x32_bf16 v[52:55], v[238:241], v[186:189], v[52:55]
	v_mfma_f32_16x16x32_bf16 v[40:43], v[230:233], v[194:197], v[40:43]
	v_mfma_f32_16x16x32_bf16 v[36:39], v[238:241], v[194:197], v[36:39]
	v_mfma_f32_16x16x32_bf16 v[24:27], v[230:233], v[214:217], v[24:27]
	v_mfma_f32_16x16x32_bf16 v[20:23], v[238:241], v[214:217], v[20:23]
	v_mfma_f32_16x16x32_bf16 v[8:11], v[230:233], v[222:225], v[8:11]
	v_mfma_f32_16x16x32_bf16 v[4:7], v[238:241], v[222:225], v[4:7]
	v_mfma_f32_16x16x32_bf16 v[56:59], v[234:237], v[190:193], v[56:59]
	v_mfma_f32_16x16x32_bf16 v[52:55], v[242:245], v[190:193], v[52:55]
	v_mfma_f32_16x16x32_bf16 v[40:43], v[234:237], v[198:201], v[40:43]
	v_mfma_f32_16x16x32_bf16 v[36:39], v[242:245], v[198:201], v[36:39]
	v_mfma_f32_16x16x32_bf16 v[24:27], v[234:237], v[218:221], v[24:27]
	v_mfma_f32_16x16x32_bf16 v[20:23], v[242:245], v[218:221], v[20:23]
	v_mfma_f32_16x16x32_bf16 v[8:11], v[234:237], v[226:229], v[8:11]
	v_mfma_f32_16x16x32_bf16 v[4:7], v[242:245], v[226:229], v[4:7]
	s_add_i32 s48, 0, 0x18000
	v_add_u32_e32 v182, s48, v163
	s_barrier
	ds_read_b128 v[142:145], v182
	ds_read_b128 v[174:177], v182 offset:1024
	ds_read_b128 v[178:181], v182 offset:2048
	ds_read_b128 v[182:185], v182 offset:3072
	s_add_u32 s24, s24, 0x80000
	s_addc_u32 s25, s25, 0
	s_mov_b32 m0, s36
	v_lshl_add_u64 v[230:231], s[24:25], 0, v[132:133]
	ds_read_b128 v[186:189], v173 offset:32768
	ds_read_b128 v[190:193], v173 offset:33792
	ds_read_b128 v[194:197], v173 offset:34816
	ds_read_b128 v[198:201], v173 offset:35840
	ds_read_b128 v[214:217], v173 offset:36864
	ds_read_b128 v[218:221], v173 offset:37888
	ds_read_b128 v[222:225], v173 offset:38912
	ds_read_b128 v[226:229], v173 offset:39936
	global_load_lds_dwordx4 v[230:231], off
	v_lshl_add_u64 v[230:231], s[24:25], 0, v[134:135]
	s_mov_b32 m0, s37
	s_nop 0
	global_load_lds_dwordx4 v[230:231], off
	s_waitcnt lgkmcnt(8)
	s_barrier
	s_waitcnt lgkmcnt(0)
	s_waitcnt lgkmcnt(0)
	v_mfma_f32_16x16x32_bf16 v[128:131], v[142:145], v[186:189], v[128:131]
	v_mfma_f32_16x16x32_bf16 v[124:127], v[178:181], v[186:189], v[124:127]
	v_mfma_f32_16x16x32_bf16 v[112:115], v[142:145], v[194:197], v[112:115]
	v_mfma_f32_16x16x32_bf16 v[108:111], v[178:181], v[194:197], v[108:111]
	v_mfma_f32_16x16x32_bf16 v[96:99], v[142:145], v[214:217], v[96:99]
	v_mfma_f32_16x16x32_bf16 v[92:95], v[178:181], v[214:217], v[92:95]
	v_mfma_f32_16x16x32_bf16 v[80:83], v[142:145], v[222:225], v[80:83]
	v_mfma_f32_16x16x32_bf16 v[76:79], v[178:181], v[222:225], v[76:79]
	v_mfma_f32_16x16x32_bf16 v[128:131], v[174:177], v[190:193], v[128:131]
	v_mfma_f32_16x16x32_bf16 v[124:127], v[182:185], v[190:193], v[124:127]
	v_mfma_f32_16x16x32_bf16 v[112:115], v[174:177], v[198:201], v[112:115]
	v_mfma_f32_16x16x32_bf16 v[108:111], v[182:185], v[198:201], v[108:111]
	v_mfma_f32_16x16x32_bf16 v[96:99], v[174:177], v[218:221], v[96:99]
	v_mfma_f32_16x16x32_bf16 v[92:95], v[182:185], v[218:221], v[92:95]
	v_mfma_f32_16x16x32_bf16 v[80:83], v[174:177], v[226:229], v[80:83]
	v_mfma_f32_16x16x32_bf16 v[76:79], v[182:185], v[226:229], v[76:79]
	s_barrier
	s_add_i32 s24, 0, 0x1c000
	s_add_i32 s25, s48, s31
	v_add_u32_e32 v242, s24, v163
	v_lshl_add_u64 v[146:147], v[146:147], 0, s[34:35]
	s_mov_b32 m0, s25
	ds_read_b128 v[230:233], v242
	ds_read_b128 v[234:237], v242 offset:1024
	ds_read_b128 v[238:241], v242 offset:2048
	ds_read_b128 v[242:245], v242 offset:3072
	global_load_lds_dwordx4 v[146:147], off
	v_lshl_add_u64 v[146:147], v[170:171], 0, s[34:35]
	s_add_i32 m0, s25, 0x2000
	s_nop 0
	global_load_lds_dwordx4 v[146:147], off
	s_barrier
	s_waitcnt lgkmcnt(0)
	s_waitcnt lgkmcnt(0)
	v_mfma_f32_16x16x32_bf16 v[120:123], v[230:233], v[186:189], v[120:123]
	v_mfma_f32_16x16x32_bf16 v[116:119], v[238:241], v[186:189], v[116:119]
	v_mfma_f32_16x16x32_bf16 v[104:107], v[230:233], v[194:197], v[104:107]
	v_mfma_f32_16x16x32_bf16 v[100:103], v[238:241], v[194:197], v[100:103]
	v_mfma_f32_16x16x32_bf16 v[88:91], v[230:233], v[214:217], v[88:91]
	v_mfma_f32_16x16x32_bf16 v[84:87], v[238:241], v[214:217], v[84:87]
	v_mfma_f32_16x16x32_bf16 v[72:75], v[230:233], v[222:225], v[72:75]
	v_mfma_f32_16x16x32_bf16 v[68:71], v[238:241], v[222:225], v[68:71]
	v_mfma_f32_16x16x32_bf16 v[120:123], v[234:237], v[190:193], v[120:123]
	v_mfma_f32_16x16x32_bf16 v[116:119], v[242:245], v[190:193], v[116:119]
	v_mfma_f32_16x16x32_bf16 v[104:107], v[234:237], v[198:201], v[104:107]
	v_mfma_f32_16x16x32_bf16 v[100:103], v[242:245], v[198:201], v[100:103]
	v_mfma_f32_16x16x32_bf16 v[88:91], v[234:237], v[218:221], v[88:91]
	v_mfma_f32_16x16x32_bf16 v[84:87], v[242:245], v[218:221], v[84:87]
	v_mfma_f32_16x16x32_bf16 v[72:75], v[234:237], v[226:229], v[72:75]
	v_mfma_f32_16x16x32_bf16 v[68:71], v[242:245], v[226:229], v[68:71]
	s_mov_b32 m0, s38
	v_lshl_add_u64 v[146:147], v[246:247], 0, s[34:35]
	s_barrier
	ds_read_b128 v[186:189], v173 offset:49152
	ds_read_b128 v[190:193], v173 offset:50176
	ds_read_b128 v[194:197], v173 offset:51200
	ds_read_b128 v[198:201], v173 offset:52224
	ds_read_b128 v[214:217], v173 offset:53248
	ds_read_b128 v[218:221], v173 offset:54272
	ds_read_b128 v[222:225], v173 offset:55296
	ds_read_b128 v[226:229], v173 offset:56320
	global_load_lds_dwordx4 v[146:147], off
	v_lshl_add_u64 v[146:147], v[248:249], 0, s[34:35]
	s_mov_b32 m0, s39
	s_nop 0
	global_load_lds_dwordx4 v[146:147], off
	s_barrier
; __device__ __forceinline__ unsigned pack2(float lo, float hi) { unsigned r; asm("v_cvt_pk_bf16_f32 %0, %1, %2" : "=v"(r) : "v"(lo), "v"(hi)); return r; }
; #define PG8_STAGE(bufoff, gbase, voff) do { _Pragma("unroll") for (int _i = 0; _i < 2; ++_i) \
;         __builtin_amdgcn_global_load_lds((const unsigned*)((const char*)(gbase) + (voff)[_i]), (LAS unsigned*)(lds + (bufoff) + ldsw + _i * 8192), 16, 0, 0); } while (0)
; #define PG8_MMA(ai, bj, At, Bt) do { __builtin_amdgcn_s_setprio(1); _Pragma("unroll") for (int m = 0; m < 4; ++m) _Pragma("unroll") for (int n = 0; n < 2; ++n) _Pragma("unroll") for (int k = 0; k < 2; ++k) \
;         acc[ai][bj][m][n] = __builtin_amdgcn_mfma_f32_16x16x32_bf16(Bt[n][k], At[m][k], acc[ai][bj][m][n], 0, 0, 0); __builtin_amdgcn_s_setprio(0); } while (0)
; #define PG8_WAIT_V(n) asm volatile("s_waitcnt vmcnt(" #n ")" ::: "memory")
; #define PG8_BAR __builtin_amdgcn_s_barrier()
; template <class Epi>
; __device__ __forceinline__ void gemm_phase(LAS unsigned char* lds, const Gemm g, const StaticOrder& S, const Epi& E) {
;     ...
;             PG8_STAGE(PG8_SB(1, 1), b3 + hstep, voffB);
;             PG8_WAIT_V(6); PG8_BAR; PG8_MMA(1, 1, At, B1); PG8_BAR;
;     __device__ __forceinline__ void operator()(const AccT& acc, const pg8::Unit& u, int wr, int wc, int fr, int fq) const {
;         const int row0 = u.pm * 256 + wr * 64 + fr, col0 = u.pn * 256 + wc * 32 + 8 * fq;
; #pragma unroll
;         for (int ai = 0; ai < 2; ++ai)
; #pragma unroll
;             for (int m = 0; m < 4; ++m) {
;                 const int row = row0 + ai * 128 + m * 16;
;                 const float r2 = rsqrtf(SS2[row] * (1.f / 2048.f) + EPS);
;                 bf16_t* rowp = UP + (size_t)row * N3 + col0;
; #pragma unroll
;                 for (int bj = 0; bj < 2; ++bj) {
;                     const f32x4 v0 = acc[ai][bj][m][0] * r2, v1 = acc[ai][bj][m][1] * r2;
;                     u32x4 o; o[0] = pack2(v0[0], v0[1]); o[1] = pack2(v0[2], v0[3]); o[2] = pack2(v1[0], v1[1]); o[3] = pack2(v1[2], v1[3]);
;                     *(u32x4*)(rowp + bj * 128) = o;
	s_waitcnt lgkmcnt(0)
	s_waitcnt lgkmcnt(0)
	v_mfma_f32_16x16x32_bf16 v[64:67], v[142:145], v[186:189], v[64:67]
	v_mfma_f32_16x16x32_bf16 v[60:63], v[178:181], v[186:189], v[60:63]
	v_mfma_f32_16x16x32_bf16 v[48:51], v[142:145], v[194:197], v[48:51]
	v_mfma_f32_16x16x32_bf16 v[44:47], v[178:181], v[194:197], v[44:47]
	v_mfma_f32_16x16x32_bf16 v[32:35], v[142:145], v[214:217], v[32:35]
	v_mfma_f32_16x16x32_bf16 v[28:31], v[178:181], v[214:217], v[28:31]
	v_mfma_f32_16x16x32_bf16 v[16:19], v[142:145], v[222:225], v[16:19]
	v_mfma_f32_16x16x32_bf16 v[12:15], v[178:181], v[222:225], v[12:15]
	v_mfma_f32_16x16x32_bf16 v[64:67], v[174:177], v[190:193], v[64:67]
	v_mfma_f32_16x16x32_bf16 v[60:63], v[182:185], v[190:193], v[60:63]
	v_mfma_f32_16x16x32_bf16 v[48:51], v[174:177], v[198:201], v[48:51]
	v_mfma_f32_16x16x32_bf16 v[44:47], v[182:185], v[198:201], v[44:47]
	v_mfma_f32_16x16x32_bf16 v[32:35], v[174:177], v[218:221], v[32:35]
	v_mfma_f32_16x16x32_bf16 v[28:31], v[182:185], v[218:221], v[28:31]
	v_mfma_f32_16x16x32_bf16 v[16:19], v[174:177], v[226:229], v[16:19]
	v_mfma_f32_16x16x32_bf16 v[12:15], v[182:185], v[226:229], v[12:15]
	s_barrier
	s_add_u32 s22, s22, 0x80080
	s_addc_u32 s23, s23, 0
	s_add_i32 s24, s24, s31
	v_lshl_add_u64 v[142:143], s[22:23], 0, v[148:149]
	s_mov_b32 m0, s24
	s_nop 0
	global_load_lds_dwordx4 v[142:143], off
	v_lshl_add_u64 v[142:143], s[22:23], 0, v[136:137]
	s_add_i32 m0, s24, 0x2000
	s_nop 0
	global_load_lds_dwordx4 v[142:143], off
	s_waitcnt vmcnt(6)
	s_barrier
	v_mfma_f32_16x16x32_bf16 v[56:59], v[230:233], v[186:189], v[56:59]
	v_mfma_f32_16x16x32_bf16 v[52:55], v[238:241], v[186:189], v[52:55]
	v_mfma_f32_16x16x32_bf16 v[40:43], v[230:233], v[194:197], v[40:43]
	v_mfma_f32_16x16x32_bf16 v[36:39], v[238:241], v[194:197], v[36:39]
	v_mfma_f32_16x16x32_bf16 v[24:27], v[230:233], v[214:217], v[24:27]
	v_mfma_f32_16x16x32_bf16 v[20:23], v[238:241], v[214:217], v[20:23]
	v_mfma_f32_16x16x32_bf16 v[8:11], v[230:233], v[222:225], v[8:11]
	v_mfma_f32_16x16x32_bf16 v[4:7], v[238:241], v[222:225], v[4:7]
	v_mfma_f32_16x16x32_bf16 v[56:59], v[234:237], v[190:193], v[56:59]
	v_mfma_f32_16x16x32_bf16 v[52:55], v[242:245], v[190:193], v[52:55]
	v_mfma_f32_16x16x32_bf16 v[40:43], v[234:237], v[198:201], v[40:43]
	v_mfma_f32_16x16x32_bf16 v[36:39], v[242:245], v[198:201], v[36:39]
	v_mfma_f32_16x16x32_bf16 v[24:27], v[234:237], v[218:221], v[24:27]
	v_mfma_f32_16x16x32_bf16 v[20:23], v[242:245], v[218:221], v[20:23]
	v_mfma_f32_16x16x32_bf16 v[8:11], v[234:237], v[226:229], v[8:11]
	v_mfma_f32_16x16x32_bf16 v[4:7], v[242:245], v[226:229], v[4:7]
	s_add_i32 s47, s47, 2
	s_add_u32 s20, s20, 0x100
	s_addc_u32 s21, s21, 0
	s_add_u32 s44, s44, 0x100
	s_addc_u32 s46, s46, 0
	s_cmp_gt_u32 s47, 29
	s_barrier
	s_cbranch_scc0 .LBB0_98
	s_mov_b32 s13, 0x800000
	v_lshl_add_u32 v142, s18, 8, v153
	v_ashrrev_i32_e32 v143, 31, v142
	v_lshl_add_u64 v[144:145], v[142:143], 2, s[6:7]
	global_load_dword v246, v[144:145], off
	global_load_dword v247, v[144:145], off offset:64
	global_load_dword v248, v[144:145], off offset:128
	global_load_dword v249, v[144:145], off offset:192
	global_load_dword v250, v[144:145], off offset:512
	global_load_dword v251, v[144:145], off offset:576
	global_load_dword v252, v[144:145], off offset:640
	global_load_dword v253, v[144:145], off offset:704
	v_lshl_or_b32 v170, s41, 8, v172
	v_ashrrev_i32_e32 v171, 31, v170
	s_movk_i32 s9, 0x5800
	v_lshlrev_b64 v[170:171], 1, v[170:171]
	s_mov_b32 s18, s12
	s_mov_b32 s41, s8
	s_mov_b64 s[22:23], s[16:17]
	s_waitcnt vmcnt(0)
	v_mov_b32_e32 v143, v246
	v_fmamk_f32 v143, v143, 0x3a000000, v202
	v_cmp_gt_f32_e32 vcc, s13, v143
	v_mul_f32_e32 v146, 0x4b800000, v143
	s_nop 0
	v_cndmask_b32_e32 v143, v143, v146, vcc
	v_rsq_f32_e32 v143, v143
	s_nop 0
	v_mul_f32_e32 v146, 0x45800000, v143
	v_cndmask_b32_e32 v174, v143, v146, vcc
	v_mov_b64_e32 v[146:147], s[4:5]
	v_mad_i64_i32 v[176:177], s[20:21], v142, s9, v[146:147]
	v_lshl_add_u64 v[176:177], v[176:177], 0, v[170:171]
	v_pk_mul_f32 v[130:131], v[130:131], v[174:175] op_sel_hi:[1,0]
	v_pk_mul_f32 v[128:129], v[128:129], v[174:175] op_sel_hi:[1,0]
	v_pk_mul_f32 v[178:179], v[126:127], v[174:175] op_sel_hi:[1,0]
	v_pk_mul_f32 v[126:127], v[124:125], v[174:175] op_sel_hi:[1,0]
	v_cvt_pk_bf16_f32 v124, v128, v129
	v_cvt_pk_bf16_f32 v125, v130, v131
	v_pk_mul_f32 v[120:121], v[120:121], v[174:175] op_sel_hi:[1,0]
	v_cvt_pk_bf16_f32 v126, v126, v127
	v_cvt_pk_bf16_f32 v127, v178, v179
	global_store_dwordx4 v[176:177], v[124:127], off
	v_pk_mul_f32 v[122:123], v[122:123], v[174:175] op_sel_hi:[1,0]
	s_nop 0
	v_pk_mul_f32 v[124:125], v[118:119], v[174:175] op_sel_hi:[1,0]
	v_pk_mul_f32 v[118:119], v[116:117], v[174:175] op_sel_hi:[1,0]
	v_cvt_pk_bf16_f32 v116, v120, v121
	v_cvt_pk_bf16_f32 v117, v122, v123
	s_nop 0
	v_cvt_pk_bf16_f32 v118, v118, v119
	v_cvt_pk_bf16_f32 v119, v124, v125
	global_store_dwordx4 v[176:177], v[116:119], off offset:256
	s_nop 1
	v_or_b32_e32 v116, 16, v142
	v_ashrrev_i32_e32 v117, 31, v116
	v_lshl_add_u64 v[118:119], v[116:117], 2, s[6:7]
	s_nop 1
	v_mov_b32_e32 v117, v247
	v_fmamk_f32 v117, v117, 0x3a000000, v202
	v_cmp_gt_f32_e32 vcc, s13, v117
	v_mul_f32_e32 v118, 0x4b800000, v117
	s_nop 0
	v_cndmask_b32_e32 v117, v117, v118, vcc
	v_rsq_f32_e32 v117, v117
	s_nop 0
	v_mul_f32_e32 v118, 0x45800000, v117
	v_cndmask_b32_e32 v118, v117, v118, vcc
	v_mad_i64_i32 v[116:117], s[20:21], v116, s9, v[146:147]
	v_lshl_add_u64 v[116:117], v[116:117], 0, v[170:171]
	v_pk_mul_f32 v[114:115], v[114:115], v[118:119] op_sel_hi:[1,0]
	v_pk_mul_f32 v[112:113], v[112:113], v[118:119] op_sel_hi:[1,0]
; __device__ __forceinline__ unsigned pack2(float lo, float hi) { unsigned r; asm("v_cvt_pk_bf16_f32 %0, %1, %2" : "=v"(r) : "v"(lo), "v"(hi)); return r; }
;     __device__ __forceinline__ void operator()(const AccT& acc, const pg8::Unit& u, int wr, int wc, int fr, int fq) const {
;     ...
;         for (int ai = 0; ai < 2; ++ai)
; #pragma unroll
;             for (int m = 0; m < 4; ++m) {
;                 const int row = row0 + ai * 128 + m * 16;
;                 const float r2 = rsqrtf(SS2[row] * (1.f / 2048.f) + EPS);
;                 bf16_t* rowp = UP + (size_t)row * N3 + col0;
; #pragma unroll
;                 for (int bj = 0; bj < 2; ++bj) {
;                     const f32x4 v0 = acc[ai][bj][m][0] * r2, v1 = acc[ai][bj][m][1] * r2;
;                     u32x4 o; o[0] = pack2(v0[0], v0[1]); o[1] = pack2(v0[2], v0[3]); o[2] = pack2(v1[0], v1[1]); o[3] = pack2(v1[2], v1[3]);
;                     *(u32x4*)(rowp + bj * 128) = o;
;                 }
;             }
	v_pk_mul_f32 v[120:121], v[110:111], v[118:119] op_sel_hi:[1,0]
	v_pk_mul_f32 v[110:111], v[108:109], v[118:119] op_sel_hi:[1,0]
	v_cvt_pk_bf16_f32 v108, v112, v113
	v_cvt_pk_bf16_f32 v109, v114, v115
	v_pk_mul_f32 v[104:105], v[104:105], v[118:119] op_sel_hi:[1,0]
	v_cvt_pk_bf16_f32 v110, v110, v111
	v_cvt_pk_bf16_f32 v111, v120, v121
	global_store_dwordx4 v[116:117], v[108:111], off
	v_pk_mul_f32 v[106:107], v[106:107], v[118:119] op_sel_hi:[1,0]
	s_nop 0
	v_pk_mul_f32 v[108:109], v[102:103], v[118:119] op_sel_hi:[1,0]
	v_pk_mul_f32 v[102:103], v[100:101], v[118:119] op_sel_hi:[1,0]
	v_cvt_pk_bf16_f32 v100, v104, v105
	v_cvt_pk_bf16_f32 v101, v106, v107
	s_nop 0
	v_cvt_pk_bf16_f32 v102, v102, v103
	v_cvt_pk_bf16_f32 v103, v108, v109
	global_store_dwordx4 v[116:117], v[100:103], off offset:256
	s_nop 1
	v_or_b32_e32 v100, 32, v142
	v_ashrrev_i32_e32 v101, 31, v100
	v_lshl_add_u64 v[102:103], v[100:101], 2, s[6:7]
	s_nop 1
	v_mov_b32_e32 v101, v248
	v_fmamk_f32 v101, v101, 0x3a000000, v202
	v_cmp_gt_f32_e32 vcc, s13, v101
	v_mul_f32_e32 v102, 0x4b800000, v101
	s_nop 0
	v_cndmask_b32_e32 v101, v101, v102, vcc
	v_rsq_f32_e32 v101, v101
	s_nop 0
	v_mul_f32_e32 v102, 0x45800000, v101
	v_cndmask_b32_e32 v102, v101, v102, vcc
	v_mad_i64_i32 v[100:101], s[20:21], v100, s9, v[146:147]
	v_lshl_add_u64 v[100:101], v[100:101], 0, v[170:171]
	v_pk_mul_f32 v[98:99], v[98:99], v[102:103] op_sel_hi:[1,0]
	v_pk_mul_f32 v[96:97], v[96:97], v[102:103] op_sel_hi:[1,0]
	v_pk_mul_f32 v[104:105], v[94:95], v[102:103] op_sel_hi:[1,0]
	v_pk_mul_f32 v[94:95], v[92:93], v[102:103] op_sel_hi:[1,0]
	v_cvt_pk_bf16_f32 v92, v96, v97
	v_cvt_pk_bf16_f32 v93, v98, v99
	v_pk_mul_f32 v[88:89], v[88:89], v[102:103] op_sel_hi:[1,0]
	v_cvt_pk_bf16_f32 v94, v94, v95
	v_cvt_pk_bf16_f32 v95, v104, v105
	global_store_dwordx4 v[100:101], v[92:95], off
	v_pk_mul_f32 v[90:91], v[90:91], v[102:103] op_sel_hi:[1,0]
	s_nop 0
	v_pk_mul_f32 v[92:93], v[86:87], v[102:103] op_sel_hi:[1,0]
	v_pk_mul_f32 v[86:87], v[84:85], v[102:103] op_sel_hi:[1,0]
	v_cvt_pk_bf16_f32 v84, v88, v89
	v_cvt_pk_bf16_f32 v85, v90, v91
	s_nop 0
	v_cvt_pk_bf16_f32 v86, v86, v87
	v_cvt_pk_bf16_f32 v87, v92, v93
	global_store_dwordx4 v[100:101], v[84:87], off offset:256
	s_nop 1
	v_or_b32_e32 v84, 48, v142
	v_ashrrev_i32_e32 v85, 31, v84
	v_lshl_add_u64 v[86:87], v[84:85], 2, s[6:7]
	s_nop 1
	v_mov_b32_e32 v85, v249
	v_fmamk_f32 v85, v85, 0x3a000000, v202
	v_cmp_gt_f32_e32 vcc, s13, v85
	v_mul_f32_e32 v86, 0x4b800000, v85
	s_nop 0
	v_cndmask_b32_e32 v85, v85, v86, vcc
	v_rsq_f32_e32 v85, v85
	s_nop 0
	v_mul_f32_e32 v86, 0x45800000, v85
	v_cndmask_b32_e32 v86, v85, v86, vcc
	v_mad_i64_i32 v[84:85], s[20:21], v84, s9, v[146:147]
	v_lshl_add_u64 v[84:85], v[84:85], 0, v[170:171]
	v_pk_mul_f32 v[82:83], v[82:83], v[86:87] op_sel_hi:[1,0]
	v_pk_mul_f32 v[80:81], v[80:81], v[86:87] op_sel_hi:[1,0]
	v_pk_mul_f32 v[88:89], v[78:79], v[86:87] op_sel_hi:[1,0]
	v_pk_mul_f32 v[78:79], v[76:77], v[86:87] op_sel_hi:[1,0]
	v_cvt_pk_bf16_f32 v76, v80, v81
	v_cvt_pk_bf16_f32 v77, v82, v83
	v_pk_mul_f32 v[74:75], v[74:75], v[86:87] op_sel_hi:[1,0]
	v_cvt_pk_bf16_f32 v78, v78, v79
	v_cvt_pk_bf16_f32 v79, v88, v89
	global_store_dwordx4 v[84:85], v[76:79], off
	v_pk_mul_f32 v[72:73], v[72:73], v[86:87] op_sel_hi:[1,0]
	s_nop 0
	v_pk_mul_f32 v[76:77], v[70:71], v[86:87] op_sel_hi:[1,0]
	v_pk_mul_f32 v[70:71], v[68:69], v[86:87] op_sel_hi:[1,0]
	v_cvt_pk_bf16_f32 v68, v72, v73
	v_cvt_pk_bf16_f32 v69, v74, v75
	s_nop 0
	v_cvt_pk_bf16_f32 v70, v70, v71
	v_cvt_pk_bf16_f32 v71, v76, v77
	global_store_dwordx4 v[84:85], v[68:71], off offset:256
	s_nop 1
	v_mov_b32_e32 v68, v250
	s_nop 0
	v_add_u32_e32 v69, 0x80, v142
	v_fmamk_f32 v68, v68, 0x3a000000, v202
	v_cmp_gt_f32_e32 vcc, s13, v68
	v_mul_f32_e32 v70, 0x4b800000, v68
	s_nop 0
	v_cndmask_b32_e32 v68, v68, v70, vcc
	v_rsq_f32_e32 v68, v68
	s_nop 0
	v_mul_f32_e32 v70, 0x45800000, v68
	v_cndmask_b32_e32 v68, v68, v70, vcc
	v_mad_i64_i32 v[70:71], s[20:21], v69, s9, v[146:147]
	v_lshl_add_u64 v[70:71], v[70:71], 0, v[170:171]
	v_pk_mul_f32 v[66:67], v[66:67], v[68:69] op_sel_hi:[1,0]
	v_pk_mul_f32 v[64:65], v[64:65], v[68:69] op_sel_hi:[1,0]
	v_pk_mul_f32 v[72:73], v[62:63], v[68:69] op_sel_hi:[1,0]
	v_pk_mul_f32 v[62:63], v[60:61], v[68:69] op_sel_hi:[1,0]
	v_cvt_pk_bf16_f32 v60, v64, v65
	v_cvt_pk_bf16_f32 v61, v66, v67
	v_pk_mul_f32 v[58:59], v[58:59], v[68:69] op_sel_hi:[1,0]
	v_cvt_pk_bf16_f32 v62, v62, v63
	v_cvt_pk_bf16_f32 v63, v72, v73
; __device__ __forceinline__ unsigned pack2(float lo, float hi) { unsigned r; asm("v_cvt_pk_bf16_f32 %0, %1, %2" : "=v"(r) : "v"(lo), "v"(hi)); return r; }
; #define PG8_WAIT_V(n) asm volatile("s_waitcnt vmcnt(" #n ")" ::: "memory")
; #define PG8_BAR __builtin_amdgcn_s_barrier()
; template <class Epi>
; __device__ __forceinline__ void gemm_phase(LAS unsigned char* lds, const Gemm g, const StaticOrder& S, const Epi& E) {
;     ...
;         if (!has_next) break;
; #pragma unroll
;         for (int a = 0; a < 2; ++a)
; #pragma unroll
;             for (int b = 0; b < 2; ++b)
; #pragma unroll
;                 for (int m = 0; m < 4; ++m)
; #pragma unroll
;                     for (int n = 0; n < 2; ++n) acc[a][b][m][n] = (f32x4){0.f, 0.f, 0.f, 0.f};
;         cur = nxt; cA = nA; cB = nB; ++ui;
;     }
;     PG8_WAIT_V(0);
;     if (wr == 0) PG8_BAR;
;     PG8_BAR;
;     __device__ __forceinline__ void operator()(const AccT& acc, const pg8::Unit& u, int wr, int wc, int fr, int fq) const {
;     ...
;         for (int ai = 0; ai < 2; ++ai)
; #pragma unroll
;             for (int m = 0; m < 4; ++m) {
;                 const int row = row0 + ai * 128 + m * 16;
;                 const float r2 = rsqrtf(SS2[row] * (1.f / 2048.f) + EPS);
;                 bf16_t* rowp = UP + (size_t)row * N3 + col0;
; #pragma unroll
;                 for (int bj = 0; bj < 2; ++bj) {
;                     const f32x4 v0 = acc[ai][bj][m][0] * r2, v1 = acc[ai][bj][m][1] * r2;
;                     u32x4 o; o[0] = pack2(v0[0], v0[1]); o[1] = pack2(v0[2], v0[3]); o[2] = pack2(v1[0], v1[1]); o[3] = pack2(v1[2], v1[3]);
;                     *(u32x4*)(rowp + bj * 128) = o;
;                 }
;             }
	global_store_dwordx4 v[70:71], v[60:63], off
	v_pk_mul_f32 v[56:57], v[56:57], v[68:69] op_sel_hi:[1,0]
	s_nop 0
	v_pk_mul_f32 v[60:61], v[54:55], v[68:69] op_sel_hi:[1,0]
	v_pk_mul_f32 v[54:55], v[52:53], v[68:69] op_sel_hi:[1,0]
	v_cvt_pk_bf16_f32 v52, v56, v57
	v_cvt_pk_bf16_f32 v53, v58, v59
	s_nop 0
	v_cvt_pk_bf16_f32 v54, v54, v55
	v_cvt_pk_bf16_f32 v55, v60, v61
	global_store_dwordx4 v[70:71], v[52:55], off offset:256
	s_nop 1
	v_mov_b32_e32 v52, v251
	s_nop 0
	v_add_u32_e32 v53, 0x90, v142
	v_fmamk_f32 v52, v52, 0x3a000000, v202
	v_cmp_gt_f32_e32 vcc, s13, v52
	v_mul_f32_e32 v54, 0x4b800000, v52
	s_nop 0
	v_cndmask_b32_e32 v52, v52, v54, vcc
	v_rsq_f32_e32 v52, v52
	s_nop 0
	v_mul_f32_e32 v54, 0x45800000, v52
	v_cndmask_b32_e32 v52, v52, v54, vcc
	v_mad_i64_i32 v[54:55], s[20:21], v53, s9, v[146:147]
	v_lshl_add_u64 v[54:55], v[54:55], 0, v[170:171]
	v_pk_mul_f32 v[50:51], v[50:51], v[52:53] op_sel_hi:[1,0]
	v_pk_mul_f32 v[48:49], v[48:49], v[52:53] op_sel_hi:[1,0]
	v_pk_mul_f32 v[56:57], v[46:47], v[52:53] op_sel_hi:[1,0]
	v_pk_mul_f32 v[46:47], v[44:45], v[52:53] op_sel_hi:[1,0]
	v_cvt_pk_bf16_f32 v44, v48, v49
	v_cvt_pk_bf16_f32 v45, v50, v51
	v_pk_mul_f32 v[42:43], v[42:43], v[52:53] op_sel_hi:[1,0]
	v_cvt_pk_bf16_f32 v46, v46, v47
	v_cvt_pk_bf16_f32 v47, v56, v57
	global_store_dwordx4 v[54:55], v[44:47], off
	v_pk_mul_f32 v[40:41], v[40:41], v[52:53] op_sel_hi:[1,0]
	s_nop 0
	v_pk_mul_f32 v[44:45], v[38:39], v[52:53] op_sel_hi:[1,0]
	v_pk_mul_f32 v[38:39], v[36:37], v[52:53] op_sel_hi:[1,0]
	v_cvt_pk_bf16_f32 v36, v40, v41
	v_cvt_pk_bf16_f32 v37, v42, v43
	s_nop 0
	v_cvt_pk_bf16_f32 v38, v38, v39
	v_cvt_pk_bf16_f32 v39, v44, v45
	global_store_dwordx4 v[54:55], v[36:39], off offset:256
	s_nop 1
	v_mov_b32_e32 v36, v252
	s_nop 0
	v_add_u32_e32 v37, 0xa0, v142
	v_fmamk_f32 v36, v36, 0x3a000000, v202
	v_cmp_gt_f32_e32 vcc, s13, v36
	v_mul_f32_e32 v38, 0x4b800000, v36
	s_nop 0
	v_cndmask_b32_e32 v36, v36, v38, vcc
	v_rsq_f32_e32 v36, v36
	s_nop 0
	v_mul_f32_e32 v38, 0x45800000, v36
	v_cndmask_b32_e32 v36, v36, v38, vcc
	v_mad_i64_i32 v[38:39], s[20:21], v37, s9, v[146:147]
	v_lshl_add_u64 v[38:39], v[38:39], 0, v[170:171]
	v_pk_mul_f32 v[34:35], v[34:35], v[36:37] op_sel_hi:[1,0]
	v_pk_mul_f32 v[32:33], v[32:33], v[36:37] op_sel_hi:[1,0]
	v_pk_mul_f32 v[40:41], v[30:31], v[36:37] op_sel_hi:[1,0]
	v_pk_mul_f32 v[30:31], v[28:29], v[36:37] op_sel_hi:[1,0]
	v_cvt_pk_bf16_f32 v28, v32, v33
	v_cvt_pk_bf16_f32 v29, v34, v35
	v_pk_mul_f32 v[26:27], v[26:27], v[36:37] op_sel_hi:[1,0]
	v_cvt_pk_bf16_f32 v30, v30, v31
	v_cvt_pk_bf16_f32 v31, v40, v41
	global_store_dwordx4 v[38:39], v[28:31], off
	v_pk_mul_f32 v[24:25], v[24:25], v[36:37] op_sel_hi:[1,0]
	s_nop 0
	v_pk_mul_f32 v[28:29], v[22:23], v[36:37] op_sel_hi:[1,0]
	v_pk_mul_f32 v[22:23], v[20:21], v[36:37] op_sel_hi:[1,0]
	v_cvt_pk_bf16_f32 v20, v24, v25
	v_cvt_pk_bf16_f32 v21, v26, v27
	s_nop 0
	v_cvt_pk_bf16_f32 v22, v22, v23
	v_cvt_pk_bf16_f32 v23, v28, v29
	global_store_dwordx4 v[38:39], v[20:23], off offset:256
	s_nop 1
	v_mov_b32_e32 v20, v253
	s_nop 0
	v_add_u32_e32 v21, 0xb0, v142
	v_fmamk_f32 v20, v20, 0x3a000000, v202
	v_cmp_gt_f32_e32 vcc, s13, v20
	v_mul_f32_e32 v22, 0x4b800000, v20
	s_nop 0
	v_cndmask_b32_e32 v20, v20, v22, vcc
	v_rsq_f32_e32 v20, v20
	s_nop 0
	v_mul_f32_e32 v22, 0x45800000, v20
	v_cndmask_b32_e32 v20, v20, v22, vcc
	v_mad_i64_i32 v[22:23], s[20:21], v21, s9, v[146:147]
	v_lshl_add_u64 v[22:23], v[22:23], 0, v[170:171]
	v_pk_mul_f32 v[18:19], v[18:19], v[20:21] op_sel_hi:[1,0]
	v_pk_mul_f32 v[16:17], v[16:17], v[20:21] op_sel_hi:[1,0]
	v_pk_mul_f32 v[24:25], v[14:15], v[20:21] op_sel_hi:[1,0]
	v_pk_mul_f32 v[14:15], v[12:13], v[20:21] op_sel_hi:[1,0]
	v_cvt_pk_bf16_f32 v12, v16, v17
	v_cvt_pk_bf16_f32 v13, v18, v19
	s_and_b64 vcc, exec, s[0:1]
	v_cvt_pk_bf16_f32 v14, v14, v15
	v_cvt_pk_bf16_f32 v15, v24, v25
	global_store_dwordx4 v[22:23], v[12:15], off
	s_mov_b64 s[20:21], s[14:15]
	v_pk_mul_f32 v[10:11], v[10:11], v[20:21] op_sel_hi:[1,0]
	v_pk_mul_f32 v[12:13], v[6:7], v[20:21] op_sel_hi:[1,0]
	v_pk_mul_f32 v[6:7], v[4:5], v[20:21] op_sel_hi:[1,0]
	v_pk_mul_f32 v[8:9], v[8:9], v[20:21] op_sel_hi:[1,0]
	v_cvt_pk_bf16_f32 v5, v10, v11
	v_cvt_pk_bf16_f32 v6, v6, v7
	v_cvt_pk_bf16_f32 v7, v12, v13
	s_nop 0
	v_cvt_pk_bf16_f32 v4, v8, v9
	global_store_dwordx4 v[22:23], v[4:7], off offset:256
	s_cbranch_vccz .LBB0_91
	s_waitcnt vmcnt(0)
	s_mov_b32 s47, s50
	s_cmpk_gt_u32 s27, 0xff
	s_cbranch_scc1 .LBB0_102
	s_barrier

; #define PG8_STAGE(bufoff, gbase, voff) do { _Pragma("unroll") for (int _i = 0; _i < 2; ++_i) \
;         __builtin_amdgcn_global_load_lds((const unsigned*)((const char*)(gbase) + (voff)[_i]), (LAS unsigned*)(lds + (bufoff) + ldsw + _i * 8192), 16, 0, 0); } while (0)
; #define PG8_LDA(dst, b, h) do { _Pragma("unroll") for (int m = 0; m < 4; ++m) _Pragma("unroll") for (int k = 0; k < 2; ++k) dst[m][k] = *(const LAS bf16x8*)(lds + PG8_SA(b, h) + aoff + m * 2048 + k * 1024); } while (0)
; #define PG8_LDB(dst, b, h) do { _Pragma("unroll") for (int n = 0; n < 2; ++n) _Pragma("unroll") for (int k = 0; k < 2; ++k) dst[n][k] = *(const LAS bf16x8*)(lds + PG8_SB(b, h) + boff + n * 2048 + k * 1024); } while (0)
; #define PG8_MMA(ai, bj, At, Bt) do { __builtin_amdgcn_s_setprio(1); _Pragma("unroll") for (int m = 0; m < 4; ++m) _Pragma("unroll") for (int n = 0; n < 2; ++n) _Pragma("unroll") for (int k = 0; k < 2; ++k) \
;         acc[ai][bj][m][n] = __builtin_amdgcn_mfma_f32_16x16x32_bf16(Bt[n][k], At[m][k], acc[ai][bj][m][n], 0, 0, 0); __builtin_amdgcn_s_setprio(0); } while (0)
; #define PG8_WAIT_V(n) asm volatile("s_waitcnt vmcnt(" #n ")" ::: "memory")
; #define PG8_WAIT_L(n) asm volatile("s_waitcnt lgkmcnt(" #n ")" ::: "memory")
; template <class Epi>
; __device__ __forceinline__ void gemm_phase(LAS unsigned char* lds, const Gemm g, const StaticOrder& S, const Epi& E) {
;     ...
;         for (int t = 0; t < nt; t += 2) {
;             const bool last = (t == nt - 2);
;             const char* a1 = cA + (size_t)(t + 1) * kstep;
;             const char* a2 = last ? nA : cA + (size_t)(t + 2) * kstep; const char* b2 = last ? nB : cB + (size_t)(t + 2) * kstep;
;             const char* a3 = a2 + kstep; const char* b3 = b2 + kstep;
;             PG8_LDB(B0, 0, 0); PG8_SCHED; PG8_LDA(At, 0, 0); PG8_STAGE(PG8_SA(1, 1), a1 + hstep, voffA);
;             PG8_WAIT_L(8); PG8_BAR; PG8_WAIT_L(0); PG8_MMA(0, 0, At, B0); PG8_BAR; PG8_SCHED;
;             PG8_LDB(B1, 0, 1); PG8_STAGE(PG8_SB(0, 0), b2, voffB);
;             PG8_BAR; PG8_WAIT_L(0); PG8_MMA(0, 1, At, B1); PG8_BAR;
;             PG8_LDA(At, 0, 1); PG8_STAGE(PG8_SA(0, 0), a2, voffA);
;             PG8_BAR; PG8_WAIT_L(0); PG8_MMA(1, 0, At, B0); PG8_BAR; PG8_SCHED;
;             PG8_STAGE(PG8_SB(0, 1), b2 + hstep, voffB);
;             PG8_WAIT_V(6); PG8_BAR; PG8_MMA(1, 1, At, B1); PG8_BAR;
.Lprio_skip_217:
.LBB0_217:
	s_add_u32 s28, s26, 0xfff00080
	s_addc_u32 s29, s27, -1
	s_add_i32 s74, 0, 0x10000
	v_add_u32_e32 v64, s74, v163
	ds_read_b128 v[52:55], v64
	ds_read_b128 v[56:59], v64 offset:1024
	ds_read_b128 v[60:63], v64 offset:2048
	ds_read_b128 v[64:67], v64 offset:3072
	s_cmp_eq_u32 s73, 60
	s_cselect_b32 s31, s17, s29
	s_cselect_b32 s30, s23, s28
	s_cselect_b32 s29, s15, s72
	s_cselect_b32 s28, s25, s54
	v_lshl_add_u64 v[194:195], s[26:27], 0, v[178:179]
	s_add_i32 m0, s40, 0xc000
	ds_read_b128 v[182:185], v197
	ds_read_b128 v[186:189], v197 offset:1024
	ds_read_b128 v[190:193], v197 offset:2048
	ds_read_b128 v[198:201], v197 offset:3072
	ds_read_b128 v[214:217], v197 offset:4096
	ds_read_b128 v[218:221], v197 offset:5120
	ds_read_b128 v[222:225], v197 offset:6144
	ds_read_b128 v[226:229], v197 offset:7168
	global_load_lds_dwordx4 v[194:195], off
	v_lshl_add_u64 v[194:195], s[26:27], 0, v[180:181]
	s_add_i32 m0, s40, 0xe000
	s_nop 0
	global_load_lds_dwordx4 v[194:195], off
	s_waitcnt lgkmcnt(8)
	s_barrier
	s_waitcnt lgkmcnt(0)
	s_waitcnt lgkmcnt(0)
	v_mfma_f32_16x16x32_bf16 v[144:147], v[52:55], v[182:185], v[144:147]
	v_mfma_f32_16x16x32_bf16 v[140:143], v[60:63], v[182:185], v[140:143]
	v_mfma_f32_16x16x32_bf16 v[128:131], v[52:55], v[190:193], v[128:131]
	v_mfma_f32_16x16x32_bf16 v[124:127], v[60:63], v[190:193], v[124:127]
	v_mfma_f32_16x16x32_bf16 v[112:115], v[52:55], v[214:217], v[112:115]
	v_mfma_f32_16x16x32_bf16 v[108:111], v[60:63], v[214:217], v[108:111]
	v_mfma_f32_16x16x32_bf16 v[96:99], v[52:55], v[222:225], v[96:99]
	v_mfma_f32_16x16x32_bf16 v[92:95], v[60:63], v[222:225], v[92:95]
	v_mfma_f32_16x16x32_bf16 v[144:147], v[56:59], v[186:189], v[144:147]
	v_mfma_f32_16x16x32_bf16 v[140:143], v[64:67], v[186:189], v[140:143]
	v_mfma_f32_16x16x32_bf16 v[128:131], v[56:59], v[198:201], v[128:131]
	v_mfma_f32_16x16x32_bf16 v[124:127], v[64:67], v[198:201], v[124:127]
	v_mfma_f32_16x16x32_bf16 v[112:115], v[56:59], v[218:221], v[112:115]
	v_mfma_f32_16x16x32_bf16 v[108:111], v[64:67], v[218:221], v[108:111]
	v_mfma_f32_16x16x32_bf16 v[96:99], v[56:59], v[226:229], v[96:99]
	v_mfma_f32_16x16x32_bf16 v[92:95], v[64:67], v[226:229], v[92:95]
	s_barrier
	s_add_i32 s76, 0, 0x14000
	s_add_i32 s74, s74, s39
	v_add_u32_e32 v148, s76, v163
	v_lshl_add_u64 v[194:195], s[28:29], 0, v[172:173]
	s_mov_b32 m0, s74
	ds_read_b128 v[230:233], v148
	ds_read_b128 v[234:237], v148 offset:1024
	ds_read_b128 v[238:241], v148 offset:2048
	ds_read_b128 v[242:245], v148 offset:3072
	global_load_lds_dwordx4 v[194:195], off
	v_lshl_add_u64 v[246:247], s[28:29], 0, v[176:177]
	s_add_i32 m0, s74, 0x2000
	s_nop 0
	global_load_lds_dwordx4 v[246:247], off
	s_barrier
	s_waitcnt lgkmcnt(0)
	s_waitcnt lgkmcnt(0)
	v_mfma_f32_16x16x32_bf16 v[136:139], v[230:233], v[182:185], v[136:139]
	v_mfma_f32_16x16x32_bf16 v[132:135], v[238:241], v[182:185], v[132:135]
	v_mfma_f32_16x16x32_bf16 v[120:123], v[230:233], v[190:193], v[120:123]
	v_mfma_f32_16x16x32_bf16 v[116:119], v[238:241], v[190:193], v[116:119]
	v_mfma_f32_16x16x32_bf16 v[104:107], v[230:233], v[214:217], v[104:107]
	v_mfma_f32_16x16x32_bf16 v[100:103], v[238:241], v[214:217], v[100:103]
	v_mfma_f32_16x16x32_bf16 v[88:91], v[230:233], v[222:225], v[88:91]
	v_mfma_f32_16x16x32_bf16 v[84:87], v[238:241], v[222:225], v[84:87]
	v_mfma_f32_16x16x32_bf16 v[136:139], v[234:237], v[186:189], v[136:139]
	v_mfma_f32_16x16x32_bf16 v[132:135], v[242:245], v[186:189], v[132:135]
	v_mfma_f32_16x16x32_bf16 v[120:123], v[234:237], v[198:201], v[120:123]
	v_mfma_f32_16x16x32_bf16 v[116:119], v[242:245], v[198:201], v[116:119]
	v_mfma_f32_16x16x32_bf16 v[104:107], v[234:237], v[218:221], v[104:107]
	v_mfma_f32_16x16x32_bf16 v[100:103], v[242:245], v[218:221], v[100:103]
	v_mfma_f32_16x16x32_bf16 v[88:91], v[234:237], v[226:229], v[88:91]
	v_mfma_f32_16x16x32_bf16 v[84:87], v[242:245], v[226:229], v[84:87]
	s_mov_b32 m0, s40
	v_lshl_add_u64 v[248:249], s[30:31], 0, v[170:171]
	s_barrier
	ds_read_b128 v[182:185], v197 offset:16384
	ds_read_b128 v[186:189], v197 offset:17408
	ds_read_b128 v[190:193], v197 offset:18432
	ds_read_b128 v[198:201], v197 offset:19456
	ds_read_b128 v[214:217], v197 offset:20480
	ds_read_b128 v[218:221], v197 offset:21504
	ds_read_b128 v[222:225], v197 offset:22528
	ds_read_b128 v[226:229], v197 offset:23552
	global_load_lds_dwordx4 v[248:249], off
	v_lshl_add_u64 v[250:251], s[30:31], 0, v[174:175]
	s_mov_b32 m0, s41
	s_nop 0
	global_load_lds_dwordx4 v[250:251], off
	s_barrier
	s_waitcnt lgkmcnt(0)
	s_waitcnt lgkmcnt(0)
	v_mfma_f32_16x16x32_bf16 v[80:83], v[52:55], v[182:185], v[80:83]
	v_mfma_f32_16x16x32_bf16 v[76:79], v[60:63], v[182:185], v[76:79]
	v_mfma_f32_16x16x32_bf16 v[48:51], v[52:55], v[190:193], v[48:51]
	v_mfma_f32_16x16x32_bf16 v[44:47], v[60:63], v[190:193], v[44:47]
	v_mfma_f32_16x16x32_bf16 v[32:35], v[52:55], v[214:217], v[32:35]
	v_mfma_f32_16x16x32_bf16 v[28:31], v[60:63], v[214:217], v[28:31]
	v_mfma_f32_16x16x32_bf16 v[16:19], v[52:55], v[222:225], v[16:19]
	v_mfma_f32_16x16x32_bf16 v[12:15], v[60:63], v[222:225], v[12:15]
	v_mfma_f32_16x16x32_bf16 v[80:83], v[56:59], v[186:189], v[80:83]
	v_mfma_f32_16x16x32_bf16 v[76:79], v[64:67], v[186:189], v[76:79]
	v_mfma_f32_16x16x32_bf16 v[48:51], v[56:59], v[198:201], v[48:51]
	v_mfma_f32_16x16x32_bf16 v[44:47], v[64:67], v[198:201], v[44:47]
	v_mfma_f32_16x16x32_bf16 v[32:35], v[56:59], v[218:221], v[32:35]
	v_mfma_f32_16x16x32_bf16 v[28:31], v[64:67], v[218:221], v[28:31]
	v_mfma_f32_16x16x32_bf16 v[16:19], v[56:59], v[226:229], v[16:19]
	v_mfma_f32_16x16x32_bf16 v[12:15], v[64:67], v[226:229], v[12:15]
	s_barrier
; #define PG8_STAGE(bufoff, gbase, voff) do { _Pragma("unroll") for (int _i = 0; _i < 2; ++_i) \
;         __builtin_amdgcn_global_load_lds((const unsigned*)((const char*)(gbase) + (voff)[_i]), (LAS unsigned*)(lds + (bufoff) + ldsw + _i * 8192), 16, 0, 0); } while (0)
; #define PG8_LDA(dst, b, h) do { _Pragma("unroll") for (int m = 0; m < 4; ++m) _Pragma("unroll") for (int k = 0; k < 2; ++k) dst[m][k] = *(const LAS bf16x8*)(lds + PG8_SA(b, h) + aoff + m * 2048 + k * 1024); } while (0)
; #define PG8_LDB(dst, b, h) do { _Pragma("unroll") for (int n = 0; n < 2; ++n) _Pragma("unroll") for (int k = 0; k < 2; ++k) dst[n][k] = *(const LAS bf16x8*)(lds + PG8_SB(b, h) + boff + n * 2048 + k * 1024); } while (0)
; #define PG8_MMA(ai, bj, At, Bt) do { __builtin_amdgcn_s_setprio(1); _Pragma("unroll") for (int m = 0; m < 4; ++m) _Pragma("unroll") for (int n = 0; n < 2; ++n) _Pragma("unroll") for (int k = 0; k < 2; ++k) \
;         acc[ai][bj][m][n] = __builtin_amdgcn_mfma_f32_16x16x32_bf16(Bt[n][k], At[m][k], acc[ai][bj][m][n], 0, 0, 0); __builtin_amdgcn_s_setprio(0); } while (0)
; #define PG8_WAIT_V(n) asm volatile("s_waitcnt vmcnt(" #n ")" ::: "memory")
; #define PG8_WAIT_L(n) asm volatile("s_waitcnt lgkmcnt(" #n ")" ::: "memory")
; #define PG8_BAR __builtin_amdgcn_s_barrier()
; #define PG8_SCHED __builtin_amdgcn_sched_barrier(0)
; template <class Epi>
; __device__ __forceinline__ void gemm_phase(LAS unsigned char* lds, const Gemm g, const StaticOrder& S, const Epi& E) {
;     ...
;             PG8_STAGE(PG8_SB(0, 1), b2 + hstep, voffB);
;             PG8_WAIT_V(6); PG8_BAR; PG8_MMA(1, 1, At, B1); PG8_BAR;
;             PG8_LDB(B0, 1, 0); PG8_SCHED; PG8_LDA(At, 1, 0); PG8_STAGE(PG8_SA(0, 1), a2 + hstep, voffA);
;             PG8_WAIT_L(8); PG8_BAR; PG8_WAIT_L(0); PG8_MMA(0, 0, At, B0); PG8_BAR; PG8_SCHED;
;             PG8_LDB(B1, 1, 1); PG8_STAGE(PG8_SB(1, 0), b3, voffB);
;             PG8_BAR; PG8_WAIT_L(0); PG8_MMA(0, 1, At, B1); PG8_BAR;
;             PG8_LDA(At, 1, 1); PG8_STAGE(PG8_SA(1, 0), a3, voffA);
;             PG8_BAR; PG8_WAIT_L(0); PG8_MMA(1, 0, At, B0); PG8_BAR; PG8_SCHED;
	s_add_u32 s74, s28, 0x100000
	s_addc_u32 s75, s29, 0
	s_add_i32 s76, s76, s39
	v_lshl_add_u64 v[52:53], s[74:75], 0, v[172:173]
	s_mov_b32 m0, s76
	s_nop 0
	global_load_lds_dwordx4 v[52:53], off
	v_lshl_add_u64 v[52:53], s[74:75], 0, v[176:177]
	s_add_i32 m0, s76, 0x2000
	s_nop 0
	global_load_lds_dwordx4 v[52:53], off
	s_waitcnt vmcnt(6)
	s_barrier
	v_mfma_f32_16x16x32_bf16 v[40:43], v[230:233], v[190:193], v[40:43]
	v_mfma_f32_16x16x32_bf16 v[36:39], v[238:241], v[190:193], v[36:39]
	v_mfma_f32_16x16x32_bf16 v[24:27], v[230:233], v[214:217], v[24:27]
	v_mfma_f32_16x16x32_bf16 v[20:23], v[238:241], v[214:217], v[20:23]
	v_mfma_f32_16x16x32_bf16 v[8:11], v[230:233], v[222:225], v[8:11]
	v_mfma_f32_16x16x32_bf16 v[4:7], v[238:241], v[222:225], v[4:7]
	v_mfma_f32_16x16x32_bf16 v[52:55], v[230:233], v[182:185], v[72:75]
	v_mfma_f32_16x16x32_bf16 v[56:59], v[238:241], v[182:185], v[68:71]
	v_mfma_f32_16x16x32_bf16 v[40:43], v[234:237], v[198:201], v[40:43]
	v_mfma_f32_16x16x32_bf16 v[36:39], v[242:245], v[198:201], v[36:39]
	v_mfma_f32_16x16x32_bf16 v[24:27], v[234:237], v[218:221], v[24:27]
	v_mfma_f32_16x16x32_bf16 v[20:23], v[242:245], v[218:221], v[20:23]
	v_mfma_f32_16x16x32_bf16 v[8:11], v[234:237], v[226:229], v[8:11]
	v_mfma_f32_16x16x32_bf16 v[4:7], v[242:245], v[226:229], v[4:7]
	v_mfma_f32_16x16x32_bf16 v[52:55], v[234:237], v[186:189], v[52:55]
	v_mfma_f32_16x16x32_bf16 v[56:59], v[242:245], v[186:189], v[56:59]
	s_add_i32 s74, 0, 0x18000
	v_add_u32_e32 v72, s74, v163
	s_barrier
	ds_read_b128 v[60:63], v72
	ds_read_b128 v[64:67], v72 offset:1024
	ds_read_b128 v[68:71], v72 offset:2048
	ds_read_b128 v[72:75], v72 offset:3072
	s_add_u32 s30, s30, 0x100000
	s_addc_u32 s31, s31, 0
	s_mov_b32 m0, s42
	v_lshl_add_u64 v[230:231], s[30:31], 0, v[170:171]
	ds_read_b128 v[182:185], v197 offset:32768
	ds_read_b128 v[186:189], v197 offset:33792
	ds_read_b128 v[190:193], v197 offset:34816
	ds_read_b128 v[198:201], v197 offset:35840
	ds_read_b128 v[214:217], v197 offset:36864
	ds_read_b128 v[218:221], v197 offset:37888
	ds_read_b128 v[222:225], v197 offset:38912
	ds_read_b128 v[226:229], v197 offset:39936
	global_load_lds_dwordx4 v[230:231], off
	v_lshl_add_u64 v[230:231], s[30:31], 0, v[174:175]
	s_mov_b32 m0, s43
	s_nop 0
	global_load_lds_dwordx4 v[230:231], off
	s_waitcnt lgkmcnt(8)
	s_barrier
	s_waitcnt lgkmcnt(0)
	s_waitcnt lgkmcnt(0)
	v_mfma_f32_16x16x32_bf16 v[144:147], v[60:63], v[182:185], v[144:147]
	v_mfma_f32_16x16x32_bf16 v[140:143], v[68:71], v[182:185], v[140:143]
	v_mfma_f32_16x16x32_bf16 v[128:131], v[60:63], v[190:193], v[128:131]
	v_mfma_f32_16x16x32_bf16 v[124:127], v[68:71], v[190:193], v[124:127]
	v_mfma_f32_16x16x32_bf16 v[112:115], v[60:63], v[214:217], v[112:115]
	v_mfma_f32_16x16x32_bf16 v[108:111], v[68:71], v[214:217], v[108:111]
	v_mfma_f32_16x16x32_bf16 v[96:99], v[60:63], v[222:225], v[96:99]
	v_mfma_f32_16x16x32_bf16 v[92:95], v[68:71], v[222:225], v[92:95]
	v_mfma_f32_16x16x32_bf16 v[144:147], v[64:67], v[186:189], v[144:147]
	v_mfma_f32_16x16x32_bf16 v[140:143], v[72:75], v[186:189], v[140:143]
	v_mfma_f32_16x16x32_bf16 v[128:131], v[64:67], v[198:201], v[128:131]
	v_mfma_f32_16x16x32_bf16 v[124:127], v[72:75], v[198:201], v[124:127]
	v_mfma_f32_16x16x32_bf16 v[112:115], v[64:67], v[218:221], v[112:115]
	v_mfma_f32_16x16x32_bf16 v[108:111], v[72:75], v[218:221], v[108:111]
	v_mfma_f32_16x16x32_bf16 v[96:99], v[64:67], v[226:229], v[96:99]
	v_mfma_f32_16x16x32_bf16 v[92:95], v[72:75], v[226:229], v[92:95]
	s_barrier
	s_add_i32 s30, 0, 0x1c000
	s_add_i32 s31, s74, s39
	v_add_u32_e32 v148, s30, v163
	v_lshl_add_u64 v[194:195], v[194:195], 0, s[34:35]
	s_mov_b32 m0, s31
	ds_read_b128 v[230:233], v148
	ds_read_b128 v[234:237], v148 offset:1024
	ds_read_b128 v[238:241], v148 offset:2048
	ds_read_b128 v[242:245], v148 offset:3072
	global_load_lds_dwordx4 v[194:195], off
	v_lshl_add_u64 v[194:195], v[246:247], 0, s[34:35]
	s_add_i32 m0, s31, 0x2000
	s_nop 0
	global_load_lds_dwordx4 v[194:195], off
	s_barrier
	s_waitcnt lgkmcnt(0)
	s_waitcnt lgkmcnt(0)
	v_mfma_f32_16x16x32_bf16 v[136:139], v[230:233], v[182:185], v[136:139]
	v_mfma_f32_16x16x32_bf16 v[132:135], v[238:241], v[182:185], v[132:135]
	v_mfma_f32_16x16x32_bf16 v[120:123], v[230:233], v[190:193], v[120:123]
	v_mfma_f32_16x16x32_bf16 v[116:119], v[238:241], v[190:193], v[116:119]
	v_mfma_f32_16x16x32_bf16 v[104:107], v[230:233], v[214:217], v[104:107]
	v_mfma_f32_16x16x32_bf16 v[100:103], v[238:241], v[214:217], v[100:103]
	v_mfma_f32_16x16x32_bf16 v[88:91], v[230:233], v[222:225], v[88:91]
	v_mfma_f32_16x16x32_bf16 v[84:87], v[238:241], v[222:225], v[84:87]
	v_mfma_f32_16x16x32_bf16 v[136:139], v[234:237], v[186:189], v[136:139]
	v_mfma_f32_16x16x32_bf16 v[132:135], v[242:245], v[186:189], v[132:135]
	v_mfma_f32_16x16x32_bf16 v[120:123], v[234:237], v[198:201], v[120:123]
	v_mfma_f32_16x16x32_bf16 v[116:119], v[242:245], v[198:201], v[116:119]
	v_mfma_f32_16x16x32_bf16 v[104:107], v[234:237], v[218:221], v[104:107]
	v_mfma_f32_16x16x32_bf16 v[100:103], v[242:245], v[218:221], v[100:103]
	v_mfma_f32_16x16x32_bf16 v[88:91], v[234:237], v[226:229], v[88:91]
	v_mfma_f32_16x16x32_bf16 v[84:87], v[242:245], v[226:229], v[84:87]
	s_mov_b32 m0, s46
	v_lshl_add_u64 v[194:195], v[248:249], 0, s[34:35]
	s_barrier
; #define PG8_STAGE(bufoff, gbase, voff) do { _Pragma("unroll") for (int _i = 0; _i < 2; ++_i) \
;         __builtin_amdgcn_global_load_lds((const unsigned*)((const char*)(gbase) + (voff)[_i]), (LAS unsigned*)(lds + (bufoff) + ldsw + _i * 8192), 16, 0, 0); } while (0)
; #define PG8_MMA(ai, bj, At, Bt) do { __builtin_amdgcn_s_setprio(1); _Pragma("unroll") for (int m = 0; m < 4; ++m) _Pragma("unroll") for (int n = 0; n < 2; ++n) _Pragma("unroll") for (int k = 0; k < 2; ++k) \
;         acc[ai][bj][m][n] = __builtin_amdgcn_mfma_f32_16x16x32_bf16(Bt[n][k], At[m][k], acc[ai][bj][m][n], 0, 0, 0); __builtin_amdgcn_s_setprio(0); } while (0)
; #define PG8_WAIT_V(n) asm volatile("s_waitcnt vmcnt(" #n ")" ::: "memory")
; #define PG8_WAIT_L(n) asm volatile("s_waitcnt lgkmcnt(" #n ")" ::: "memory")
; #define PG8_BAR __builtin_amdgcn_s_barrier()
; template <class Epi>
; __device__ __forceinline__ void gemm_phase(LAS unsigned char* lds, const Gemm g, const StaticOrder& S, const Epi& E) {
;     ...
;             PG8_BAR; PG8_WAIT_L(0); PG8_MMA(1, 0, At, B0); PG8_BAR; PG8_SCHED;
;             PG8_STAGE(PG8_SB(1, 1), b3 + hstep, voffB);
;             PG8_WAIT_V(6); PG8_BAR; PG8_MMA(1, 1, At, B1); PG8_BAR;
;     __device__ __forceinline__ void operator()(const AccT& acc, const pg8::Unit& u, int wr, int wc, int fr, int fq) const {
;         float* H1 = (float*)(p.ws + WS_H1); bf16_t* A2 = (bf16_t*)(p.ws + WS_A2); float* SS2 = (float*)(p.ws + WS_SS2);
;         const float* nw = p.in[21];
;         const int row0 = u.pm * 256 + wr * 64 + fr, col0 = u.pn * 256 + wc * 32 + 8 * fq;
;         f32x4 w[2][2];
; #pragma unroll
;         for (int bj = 0; bj < 2; ++bj) { w[bj][0] = *(const f32x4*)(nw + col0 + bj * 128); w[bj][1] = *(const f32x4*)(nw + col0 + bj * 128 + 4); }
; #pragma unroll
;         for (int ai = 0; ai < 2; ++ai)
; #pragma unroll
;             for (int m = 0; m < 4; ++m) {
;                 const int row = row0 + ai * 128 + m * 16;
;                 const float* rp = resid_row(p, row);
;                 float ss = 0.f;
; #pragma unroll
;                 for (int bj = 0; bj < 2; ++bj) {
;                     f32x4 v0 = acc[ai][bj][m][0], v1 = acc[ai][bj][m][1];
;                     if (rp) { v0 += __builtin_nontemporal_load((const f32x4*)(rp + col0 + bj * 128)); v1 += __builtin_nontemporal_load((const f32x4*)(rp + col0 + bj * 128 + 4)); }
	ds_read_b128 v[182:185], v197 offset:49152
	ds_read_b128 v[186:189], v197 offset:50176
	ds_read_b128 v[190:193], v197 offset:51200
	ds_read_b128 v[198:201], v197 offset:52224
	ds_read_b128 v[214:217], v197 offset:53248
	ds_read_b128 v[218:221], v197 offset:54272
	ds_read_b128 v[222:225], v197 offset:55296
	ds_read_b128 v[226:229], v197 offset:56320
	global_load_lds_dwordx4 v[194:195], off
	v_lshl_add_u64 v[194:195], v[250:251], 0, s[34:35]
	s_mov_b32 m0, s47
	s_nop 0
	global_load_lds_dwordx4 v[194:195], off
	s_barrier
	s_waitcnt lgkmcnt(0)
	s_waitcnt lgkmcnt(0)
	v_mfma_f32_16x16x32_bf16 v[80:83], v[60:63], v[182:185], v[80:83]
	v_mfma_f32_16x16x32_bf16 v[76:79], v[68:71], v[182:185], v[76:79]
	v_mfma_f32_16x16x32_bf16 v[48:51], v[60:63], v[190:193], v[48:51]
	v_mfma_f32_16x16x32_bf16 v[44:47], v[68:71], v[190:193], v[44:47]
	v_mfma_f32_16x16x32_bf16 v[32:35], v[60:63], v[214:217], v[32:35]
	v_mfma_f32_16x16x32_bf16 v[28:31], v[68:71], v[214:217], v[28:31]
	v_mfma_f32_16x16x32_bf16 v[16:19], v[60:63], v[222:225], v[16:19]
	v_mfma_f32_16x16x32_bf16 v[12:15], v[68:71], v[222:225], v[12:15]
	v_mfma_f32_16x16x32_bf16 v[80:83], v[64:67], v[186:189], v[80:83]
	v_mfma_f32_16x16x32_bf16 v[76:79], v[72:75], v[186:189], v[76:79]
	v_mfma_f32_16x16x32_bf16 v[48:51], v[64:67], v[198:201], v[48:51]
	v_mfma_f32_16x16x32_bf16 v[44:47], v[72:75], v[198:201], v[44:47]
	v_mfma_f32_16x16x32_bf16 v[32:35], v[64:67], v[218:221], v[32:35]
	v_mfma_f32_16x16x32_bf16 v[28:31], v[72:75], v[218:221], v[28:31]
	v_mfma_f32_16x16x32_bf16 v[16:19], v[64:67], v[226:229], v[16:19]
	v_mfma_f32_16x16x32_bf16 v[12:15], v[72:75], v[226:229], v[12:15]
	s_barrier
	s_add_u32 s28, s28, 0x100080
	s_addc_u32 s29, s29, 0
	s_add_i32 s30, s30, s39
	v_lshl_add_u64 v[60:61], s[28:29], 0, v[172:173]
	s_mov_b32 m0, s30
	s_nop 0
	global_load_lds_dwordx4 v[60:61], off
	v_lshl_add_u64 v[60:61], s[28:29], 0, v[176:177]
	s_add_i32 m0, s30, 0x2000
	s_nop 0
	global_load_lds_dwordx4 v[60:61], off
	s_waitcnt vmcnt(6)
	s_barrier
	v_mfma_f32_16x16x32_bf16 v[52:55], v[230:233], v[182:185], v[52:55]
	v_mfma_f32_16x16x32_bf16 v[72:75], v[234:237], v[186:189], v[52:55]
	v_mfma_f32_16x16x32_bf16 v[52:55], v[238:241], v[182:185], v[56:59]
	v_mfma_f32_16x16x32_bf16 v[40:43], v[230:233], v[190:193], v[40:43]
	v_mfma_f32_16x16x32_bf16 v[36:39], v[238:241], v[190:193], v[36:39]
	v_mfma_f32_16x16x32_bf16 v[24:27], v[230:233], v[214:217], v[24:27]
	v_mfma_f32_16x16x32_bf16 v[20:23], v[238:241], v[214:217], v[20:23]
	v_mfma_f32_16x16x32_bf16 v[8:11], v[230:233], v[222:225], v[8:11]
	v_mfma_f32_16x16x32_bf16 v[4:7], v[238:241], v[222:225], v[4:7]
	v_mfma_f32_16x16x32_bf16 v[68:71], v[242:245], v[186:189], v[52:55]
	v_mfma_f32_16x16x32_bf16 v[40:43], v[234:237], v[198:201], v[40:43]
	v_mfma_f32_16x16x32_bf16 v[36:39], v[242:245], v[198:201], v[36:39]
	v_mfma_f32_16x16x32_bf16 v[24:27], v[234:237], v[218:221], v[24:27]
	v_mfma_f32_16x16x32_bf16 v[20:23], v[242:245], v[218:221], v[20:23]
	v_mfma_f32_16x16x32_bf16 v[8:11], v[234:237], v[226:229], v[8:11]
	v_mfma_f32_16x16x32_bf16 v[4:7], v[242:245], v[226:229], v[4:7]
	s_add_i32 s73, s73, 2
	s_add_u32 s26, s26, 0x100
	s_addc_u32 s27, s27, 0
	s_add_u32 s54, s54, 0x100
	s_addc_u32 s72, s72, 0
	s_cmp_gt_u32 s73, 61
	s_barrier
	s_cbranch_scc0 .LBB0_217
	v_readlane_b32 s56, v255, 11
	v_lshl_or_b32 v182, s24, 8, v196
	v_ashrrev_i32_e32 v183, 31, v182
	v_readlane_b32 s66, v255, 21
	v_readlane_b32 s67, v255, 22
	s_lshl_b32 s15, s22, 8
	s_add_i32 s15, s15, s44
	v_lshl_add_u64 v[56:57], v[182:183], 2, s[66:67]
	global_load_dwordx4 v[60:63], v[56:57], off offset:16
	global_load_dwordx4 v[64:67], v[56:57], off
	global_load_dwordx4 v[52:55], v[56:57], off offset:528
	s_nop 0
	global_load_dwordx4 v[56:59], v[56:57], off offset:512
	v_or_b32_e32 v184, s15, v153
	v_lshlrev_b32_e32 v148, 11, v184
	s_movk_i32 s17, 0x1fff
	v_and_b32_e32 v198, 0x7800, v148
	v_cmp_lt_i32_e32 vcc, s17, v184
	v_readlane_b32 s57, v255, 12
	v_readlane_b32 s58, v255, 13
	v_readlane_b32 s59, v255, 14
	v_readlane_b32 s60, v255, 15
	v_readlane_b32 s61, v255, 16
	v_readlane_b32 s62, v255, 17
	v_readlane_b32 s63, v255, 18
	v_readlane_b32 s64, v255, 19
	v_readlane_b32 s65, v255, 20
	v_readlane_b32 s68, v255, 23
	v_readlane_b32 s69, v255, 24
	v_readlane_b32 s70, v255, 25
	v_readlane_b32 s71, v255, 26
	s_and_saveexec_b64 s[22:23], vcc
	s_xor_b64 s[22:23], exec, s[22:23]
	s_cbranch_execz .LBB0_223
	s_cmpk_gt_u32 s15, 0x23ff
	s_mov_b64 s[24:25], -1
	s_cbranch_scc0 .LBB0_221
	v_readlane_b32 s56, v254, 59
	s_cmpk_lt_u32 s15, 0x2440
	v_lshlrev_b32_e32 v148, 2, v198
	v_readlane_b32 s57, v254, 60
	s_cselect_b64 vcc, -1, 0
	v_readlane_b32 s58, v254, 61
	v_lshl_add_u64 v[186:187], s[56:57], 0, v[148:149]
	v_readlane_b32 s59, v254, 62
	v_readlane_b32 s60, v254, 63
	v_readlane_b32 s61, v255, 0
	v_readlane_b32 s62, v255, 1
	v_readlane_b32 s63, v255, 2
	v_readlane_b32 s64, v255, 3
	v_readlane_b32 s65, v255, 4
	v_readlane_b32 s66, v255, 5
	v_readlane_b32 s67, v255, 6
	v_readlane_b32 s68, v255, 7
	v_readlane_b32 s69, v255, 8
	v_readlane_b32 s70, v255, 9
	v_readlane_b32 s71, v255, 10
	v_cndmask_b32_e32 v187, 0, v187, vcc
	v_cndmask_b32_e32 v186, 0, v186, vcc
	s_mov_b64 s[24:25], 0

; #define PG8_STAGE(bufoff, gbase, voff) do { _Pragma("unroll") for (int _i = 0; _i < 2; ++_i) \
;         __builtin_amdgcn_global_load_lds((const unsigned*)((const char*)(gbase) + (voff)[_i]), (LAS unsigned*)(lds + (bufoff) + ldsw + _i * 8192), 16, 0, 0); } while (0)
; #define PG8_LDA(dst, b, h) do { _Pragma("unroll") for (int m = 0; m < 4; ++m) _Pragma("unroll") for (int k = 0; k < 2; ++k) dst[m][k] = *(const LAS bf16x8*)(lds + PG8_SA(b, h) + aoff + m * 2048 + k * 1024); } while (0)
; #define PG8_LDB(dst, b, h) do { _Pragma("unroll") for (int n = 0; n < 2; ++n) _Pragma("unroll") for (int k = 0; k < 2; ++k) dst[n][k] = *(const LAS bf16x8*)(lds + PG8_SB(b, h) + boff + n * 2048 + k * 1024); } while (0)
; #define PG8_MMA(ai, bj, At, Bt) do { __builtin_amdgcn_s_setprio(1); _Pragma("unroll") for (int m = 0; m < 4; ++m) _Pragma("unroll") for (int n = 0; n < 2; ++n) _Pragma("unroll") for (int k = 0; k < 2; ++k) \
;         acc[ai][bj][m][n] = __builtin_amdgcn_mfma_f32_16x16x32_bf16(Bt[n][k], At[m][k], acc[ai][bj][m][n], 0, 0, 0); __builtin_amdgcn_s_setprio(0); } while (0)
; #define PG8_WAIT_V(n) asm volatile("s_waitcnt vmcnt(" #n ")" ::: "memory")
; #define PG8_WAIT_L(n) asm volatile("s_waitcnt lgkmcnt(" #n ")" ::: "memory")
; template <class Epi>
; __device__ __forceinline__ void gemm_phase(LAS unsigned char* lds, const Gemm g, const StaticOrder& S, const Epi& E) {
;     ...
;         for (int t = 0; t < nt; t += 2) {
;             const bool last = (t == nt - 2);
;             const char* a1 = cA + (size_t)(t + 1) * kstep;
;             const char* a2 = last ? nA : cA + (size_t)(t + 2) * kstep; const char* b2 = last ? nB : cB + (size_t)(t + 2) * kstep;
;             const char* a3 = a2 + kstep; const char* b3 = b2 + kstep;
;             PG8_LDB(B0, 0, 0); PG8_SCHED; PG8_LDA(At, 0, 0); PG8_STAGE(PG8_SA(1, 1), a1 + hstep, voffA);
;             PG8_WAIT_L(8); PG8_BAR; PG8_WAIT_L(0); PG8_MMA(0, 0, At, B0); PG8_BAR; PG8_SCHED;
;             PG8_LDB(B1, 0, 1); PG8_STAGE(PG8_SB(0, 0), b2, voffB);
;             PG8_BAR; PG8_WAIT_L(0); PG8_MMA(0, 1, At, B1); PG8_BAR;
;             PG8_LDA(At, 0, 1); PG8_STAGE(PG8_SA(0, 0), a2, voffA);
;             PG8_BAR; PG8_WAIT_L(0); PG8_MMA(1, 0, At, B0); PG8_BAR; PG8_SCHED;
;             PG8_STAGE(PG8_SB(0, 1), b2 + hstep, voffB);
;             PG8_WAIT_V(6); PG8_BAR; PG8_MMA(1, 1, At, B1); PG8_BAR;
.Lprio_skip_758:
.LBB0_758:
	s_add_u32 s22, s20, 0xfff80080
	s_addc_u32 s23, s21, -1
	s_add_i32 s48, 0, 0x10000
	v_add_u32_e32 v146, s48, v153
	ds_read_b128 v[174:177], v146
	ds_read_b128 v[178:181], v146 offset:1024
	ds_read_b128 v[182:185], v146 offset:2048
	ds_read_b128 v[186:189], v146 offset:3072
	s_cmp_eq_u32 s47, 28
	s_cselect_b32 s25, s15, s23
	s_cselect_b32 s24, s42, s22
	s_cselect_b32 s23, s13, s46
	s_cselect_b32 s22, s43, s44
	v_lshl_add_u64 v[146:147], s[20:21], 0, v[142:143]
	s_add_i32 m0, s33, 0xc000
	ds_read_b128 v[190:193], v172
	ds_read_b128 v[194:197], v172 offset:1024
	ds_read_b128 v[198:201], v172 offset:2048
	ds_read_b128 v[214:217], v172 offset:3072
	ds_read_b128 v[218:221], v172 offset:4096
	ds_read_b128 v[222:225], v172 offset:5120
	ds_read_b128 v[226:229], v172 offset:6144
	ds_read_b128 v[230:233], v172 offset:7168
	global_load_lds_dwordx4 v[146:147], off
	v_lshl_add_u64 v[146:147], s[20:21], 0, v[144:145]
	s_add_i32 m0, s33, 0xe000
	s_nop 0
	global_load_lds_dwordx4 v[146:147], off
	s_waitcnt lgkmcnt(8)
	s_barrier
	s_waitcnt lgkmcnt(0)
	s_waitcnt lgkmcnt(0)
	v_mfma_f32_16x16x32_bf16 v[128:131], v[174:177], v[190:193], v[128:131]
	v_mfma_f32_16x16x32_bf16 v[120:123], v[182:185], v[190:193], v[120:123]
	v_mfma_f32_16x16x32_bf16 v[112:115], v[174:177], v[198:201], v[112:115]
	v_mfma_f32_16x16x32_bf16 v[104:107], v[182:185], v[198:201], v[104:107]
	v_mfma_f32_16x16x32_bf16 v[96:99], v[174:177], v[218:221], v[96:99]
	v_mfma_f32_16x16x32_bf16 v[88:91], v[182:185], v[218:221], v[88:91]
	v_mfma_f32_16x16x32_bf16 v[80:83], v[174:177], v[226:229], v[80:83]
	v_mfma_f32_16x16x32_bf16 v[72:75], v[182:185], v[226:229], v[72:75]
	v_mfma_f32_16x16x32_bf16 v[128:131], v[178:181], v[194:197], v[128:131]
	v_mfma_f32_16x16x32_bf16 v[120:123], v[186:189], v[194:197], v[120:123]
	v_mfma_f32_16x16x32_bf16 v[112:115], v[178:181], v[214:217], v[112:115]
	v_mfma_f32_16x16x32_bf16 v[104:107], v[186:189], v[214:217], v[104:107]
	v_mfma_f32_16x16x32_bf16 v[96:99], v[178:181], v[222:225], v[96:99]
	v_mfma_f32_16x16x32_bf16 v[88:91], v[186:189], v[222:225], v[88:91]
	v_mfma_f32_16x16x32_bf16 v[80:83], v[178:181], v[230:233], v[80:83]
	v_mfma_f32_16x16x32_bf16 v[72:75], v[186:189], v[230:233], v[72:75]
	s_barrier
	s_add_i32 s52, 0, 0x14000
	v_add_u32_e32 v146, s52, v153
	s_add_i32 s48, s48, s30
	ds_read_b128 v[234:237], v146
	ds_read_b128 v[238:241], v146 offset:1024
	ds_read_b128 v[242:245], v146 offset:2048
	ds_read_b128 v[246:249], v146 offset:3072
	v_lshl_add_u64 v[146:147], s[22:23], 0, v[136:137]
	s_mov_b32 m0, s48
	v_lshl_add_u64 v[170:171], s[22:23], 0, v[132:133]
	global_load_lds_dwordx4 v[146:147], off
	s_add_i32 m0, s48, 0x2000
	s_nop 0
	global_load_lds_dwordx4 v[170:171], off
	s_barrier
	s_waitcnt lgkmcnt(0)
	s_waitcnt lgkmcnt(0)
	v_mfma_f32_16x16x32_bf16 v[124:127], v[234:237], v[190:193], v[124:127]
	v_mfma_f32_16x16x32_bf16 v[116:119], v[242:245], v[190:193], v[116:119]
	v_mfma_f32_16x16x32_bf16 v[108:111], v[234:237], v[198:201], v[108:111]
	v_mfma_f32_16x16x32_bf16 v[100:103], v[242:245], v[198:201], v[100:103]
	v_mfma_f32_16x16x32_bf16 v[92:95], v[234:237], v[218:221], v[92:95]
	v_mfma_f32_16x16x32_bf16 v[84:87], v[242:245], v[218:221], v[84:87]
	v_mfma_f32_16x16x32_bf16 v[76:79], v[234:237], v[226:229], v[76:79]
	v_mfma_f32_16x16x32_bf16 v[68:71], v[242:245], v[226:229], v[68:71]
	v_mfma_f32_16x16x32_bf16 v[124:127], v[238:241], v[194:197], v[124:127]
	v_mfma_f32_16x16x32_bf16 v[116:119], v[246:249], v[194:197], v[116:119]
	v_mfma_f32_16x16x32_bf16 v[108:111], v[238:241], v[214:217], v[108:111]
	v_mfma_f32_16x16x32_bf16 v[100:103], v[246:249], v[214:217], v[100:103]
	v_mfma_f32_16x16x32_bf16 v[92:95], v[238:241], v[222:225], v[92:95]
	v_mfma_f32_16x16x32_bf16 v[84:87], v[246:249], v[222:225], v[84:87]
	v_mfma_f32_16x16x32_bf16 v[76:79], v[238:241], v[230:233], v[76:79]
	v_mfma_f32_16x16x32_bf16 v[68:71], v[246:249], v[230:233], v[68:71]
	s_mov_b32 m0, s33
	v_lshl_add_u64 v[250:251], s[24:25], 0, v[138:139]
	s_barrier
	ds_read_b128 v[190:193], v172 offset:16384
	ds_read_b128 v[194:197], v172 offset:17408
	ds_read_b128 v[198:201], v172 offset:18432
	ds_read_b128 v[214:217], v172 offset:19456
	ds_read_b128 v[218:221], v172 offset:20480
	ds_read_b128 v[222:225], v172 offset:21504
	ds_read_b128 v[226:229], v172 offset:22528
	ds_read_b128 v[230:233], v172 offset:23552
	global_load_lds_dwordx4 v[250:251], off
	v_lshl_add_u64 v[252:253], s[24:25], 0, v[134:135]
	s_mov_b32 m0, s36
	s_nop 0
	global_load_lds_dwordx4 v[252:253], off
	s_barrier
	s_waitcnt lgkmcnt(0)
	s_waitcnt lgkmcnt(0)
	v_mfma_f32_16x16x32_bf16 v[64:67], v[174:177], v[190:193], v[64:67]
	v_mfma_f32_16x16x32_bf16 v[56:59], v[182:185], v[190:193], v[56:59]
	v_mfma_f32_16x16x32_bf16 v[48:51], v[174:177], v[198:201], v[48:51]
	v_mfma_f32_16x16x32_bf16 v[40:43], v[182:185], v[198:201], v[40:43]
	v_mfma_f32_16x16x32_bf16 v[32:35], v[174:177], v[218:221], v[32:35]
	v_mfma_f32_16x16x32_bf16 v[24:27], v[182:185], v[218:221], v[24:27]
	v_mfma_f32_16x16x32_bf16 v[16:19], v[174:177], v[226:229], v[16:19]
	v_mfma_f32_16x16x32_bf16 v[8:11], v[182:185], v[226:229], v[8:11]
	v_mfma_f32_16x16x32_bf16 v[64:67], v[178:181], v[194:197], v[64:67]
	v_mfma_f32_16x16x32_bf16 v[56:59], v[186:189], v[194:197], v[56:59]
	v_mfma_f32_16x16x32_bf16 v[48:51], v[178:181], v[214:217], v[48:51]
	v_mfma_f32_16x16x32_bf16 v[40:43], v[186:189], v[214:217], v[40:43]
	v_mfma_f32_16x16x32_bf16 v[32:35], v[178:181], v[222:225], v[32:35]
	v_mfma_f32_16x16x32_bf16 v[24:27], v[186:189], v[222:225], v[24:27]
	v_mfma_f32_16x16x32_bf16 v[16:19], v[178:181], v[230:233], v[16:19]
	v_mfma_f32_16x16x32_bf16 v[8:11], v[186:189], v[230:233], v[8:11]
	s_barrier
; #define PG8_STAGE(bufoff, gbase, voff) do { _Pragma("unroll") for (int _i = 0; _i < 2; ++_i) \
;         __builtin_amdgcn_global_load_lds((const unsigned*)((const char*)(gbase) + (voff)[_i]), (LAS unsigned*)(lds + (bufoff) + ldsw + _i * 8192), 16, 0, 0); } while (0)
; #define PG8_LDA(dst, b, h) do { _Pragma("unroll") for (int m = 0; m < 4; ++m) _Pragma("unroll") for (int k = 0; k < 2; ++k) dst[m][k] = *(const LAS bf16x8*)(lds + PG8_SA(b, h) + aoff + m * 2048 + k * 1024); } while (0)
; #define PG8_LDB(dst, b, h) do { _Pragma("unroll") for (int n = 0; n < 2; ++n) _Pragma("unroll") for (int k = 0; k < 2; ++k) dst[n][k] = *(const LAS bf16x8*)(lds + PG8_SB(b, h) + boff + n * 2048 + k * 1024); } while (0)
; #define PG8_MMA(ai, bj, At, Bt) do { __builtin_amdgcn_s_setprio(1); _Pragma("unroll") for (int m = 0; m < 4; ++m) _Pragma("unroll") for (int n = 0; n < 2; ++n) _Pragma("unroll") for (int k = 0; k < 2; ++k) \
;         acc[ai][bj][m][n] = __builtin_amdgcn_mfma_f32_16x16x32_bf16(Bt[n][k], At[m][k], acc[ai][bj][m][n], 0, 0, 0); __builtin_amdgcn_s_setprio(0); } while (0)
; #define PG8_WAIT_V(n) asm volatile("s_waitcnt vmcnt(" #n ")" ::: "memory")
; #define PG8_WAIT_L(n) asm volatile("s_waitcnt lgkmcnt(" #n ")" ::: "memory")
; #define PG8_BAR __builtin_amdgcn_s_barrier()
; #define PG8_SCHED __builtin_amdgcn_sched_barrier(0)
; template <class Epi>
; __device__ __forceinline__ void gemm_phase(LAS unsigned char* lds, const Gemm g, const StaticOrder& S, const Epi& E) {
;     ...
;             PG8_STAGE(PG8_SB(0, 1), b2 + hstep, voffB);
;             PG8_WAIT_V(6); PG8_BAR; PG8_MMA(1, 1, At, B1); PG8_BAR;
;             PG8_LDB(B0, 1, 0); PG8_SCHED; PG8_LDA(At, 1, 0); PG8_STAGE(PG8_SA(0, 1), a2 + hstep, voffA);
;             PG8_WAIT_L(8); PG8_BAR; PG8_WAIT_L(0); PG8_MMA(0, 0, At, B0); PG8_BAR; PG8_SCHED;
;             PG8_LDB(B1, 1, 1); PG8_STAGE(PG8_SB(1, 0), b3, voffB);
;             PG8_BAR; PG8_WAIT_L(0); PG8_MMA(0, 1, At, B1); PG8_BAR;
;             PG8_LDA(At, 1, 1); PG8_STAGE(PG8_SA(1, 0), a3, voffA);
;             PG8_BAR; PG8_WAIT_L(0); PG8_MMA(1, 0, At, B0); PG8_BAR; PG8_SCHED;
	s_add_u32 s72, s22, 0x80000
	s_addc_u32 s73, s23, 0
	s_add_i32 s48, s52, s30
	v_lshl_add_u64 v[174:175], s[72:73], 0, v[136:137]
	s_mov_b32 m0, s48
	s_nop 0
	global_load_lds_dwordx4 v[174:175], off
	v_lshl_add_u64 v[174:175], s[72:73], 0, v[132:133]
	s_add_i32 m0, s48, 0x2000
	s_nop 0
	global_load_lds_dwordx4 v[174:175], off
	s_waitcnt vmcnt(6)
	s_barrier
	v_mfma_f32_16x16x32_bf16 v[60:63], v[234:237], v[190:193], v[60:63]
	v_mfma_f32_16x16x32_bf16 v[52:55], v[242:245], v[190:193], v[52:55]
	v_mfma_f32_16x16x32_bf16 v[44:47], v[234:237], v[198:201], v[44:47]
	v_mfma_f32_16x16x32_bf16 v[36:39], v[242:245], v[198:201], v[36:39]
	v_mfma_f32_16x16x32_bf16 v[28:31], v[234:237], v[218:221], v[28:31]
	v_mfma_f32_16x16x32_bf16 v[20:23], v[242:245], v[218:221], v[20:23]
	v_mfma_f32_16x16x32_bf16 v[12:15], v[234:237], v[226:229], v[12:15]
	v_mfma_f32_16x16x32_bf16 v[4:7], v[242:245], v[226:229], v[4:7]
	v_mfma_f32_16x16x32_bf16 v[60:63], v[238:241], v[194:197], v[60:63]
	v_mfma_f32_16x16x32_bf16 v[52:55], v[246:249], v[194:197], v[52:55]
	v_mfma_f32_16x16x32_bf16 v[44:47], v[238:241], v[214:217], v[44:47]
	v_mfma_f32_16x16x32_bf16 v[36:39], v[246:249], v[214:217], v[36:39]
	v_mfma_f32_16x16x32_bf16 v[28:31], v[238:241], v[222:225], v[28:31]
	v_mfma_f32_16x16x32_bf16 v[20:23], v[246:249], v[222:225], v[20:23]
	v_mfma_f32_16x16x32_bf16 v[12:15], v[238:241], v[230:233], v[12:15]
	v_mfma_f32_16x16x32_bf16 v[4:7], v[246:249], v[230:233], v[4:7]
	s_add_i32 s48, 0, 0x18000
	v_add_u32_e32 v148, s48, v153
	s_barrier
	ds_read_b128 v[174:177], v148
	ds_read_b128 v[178:181], v148 offset:1024
	ds_read_b128 v[182:185], v148 offset:2048
	ds_read_b128 v[186:189], v148 offset:3072
	s_add_u32 s24, s24, 0x80000
	s_addc_u32 s25, s25, 0
	s_mov_b32 m0, s37
	v_lshl_add_u64 v[234:235], s[24:25], 0, v[138:139]
	ds_read_b128 v[190:193], v172 offset:32768
	ds_read_b128 v[194:197], v172 offset:33792
	ds_read_b128 v[198:201], v172 offset:34816
	ds_read_b128 v[214:217], v172 offset:35840
	ds_read_b128 v[218:221], v172 offset:36864
	ds_read_b128 v[222:225], v172 offset:37888
	ds_read_b128 v[226:229], v172 offset:38912
	ds_read_b128 v[230:233], v172 offset:39936
	global_load_lds_dwordx4 v[234:235], off
	v_lshl_add_u64 v[234:235], s[24:25], 0, v[134:135]
	s_mov_b32 m0, s38
	s_nop 0
	global_load_lds_dwordx4 v[234:235], off
	s_waitcnt lgkmcnt(8)
	s_barrier
	s_waitcnt lgkmcnt(0)
	s_waitcnt lgkmcnt(0)
	v_mfma_f32_16x16x32_bf16 v[128:131], v[174:177], v[190:193], v[128:131]
	v_mfma_f32_16x16x32_bf16 v[120:123], v[182:185], v[190:193], v[120:123]
	v_mfma_f32_16x16x32_bf16 v[112:115], v[174:177], v[198:201], v[112:115]
	v_mfma_f32_16x16x32_bf16 v[104:107], v[182:185], v[198:201], v[104:107]
	v_mfma_f32_16x16x32_bf16 v[96:99], v[174:177], v[218:221], v[96:99]
	v_mfma_f32_16x16x32_bf16 v[88:91], v[182:185], v[218:221], v[88:91]
	v_mfma_f32_16x16x32_bf16 v[80:83], v[174:177], v[226:229], v[80:83]
	v_mfma_f32_16x16x32_bf16 v[72:75], v[182:185], v[226:229], v[72:75]
	v_mfma_f32_16x16x32_bf16 v[128:131], v[178:181], v[194:197], v[128:131]
	v_mfma_f32_16x16x32_bf16 v[120:123], v[186:189], v[194:197], v[120:123]
	v_mfma_f32_16x16x32_bf16 v[112:115], v[178:181], v[214:217], v[112:115]
	v_mfma_f32_16x16x32_bf16 v[104:107], v[186:189], v[214:217], v[104:107]
	v_mfma_f32_16x16x32_bf16 v[96:99], v[178:181], v[222:225], v[96:99]
	v_mfma_f32_16x16x32_bf16 v[88:91], v[186:189], v[222:225], v[88:91]
	v_mfma_f32_16x16x32_bf16 v[80:83], v[178:181], v[230:233], v[80:83]
	v_mfma_f32_16x16x32_bf16 v[72:75], v[186:189], v[230:233], v[72:75]
	s_barrier
	s_add_i32 s24, 0, 0x1c000
	s_add_i32 s25, s48, s30
	v_add_u32_e32 v148, s24, v153
	v_lshl_add_u64 v[146:147], v[146:147], 0, s[34:35]
	s_mov_b32 m0, s25
	ds_read_b128 v[234:237], v148
	ds_read_b128 v[238:241], v148 offset:1024
	ds_read_b128 v[242:245], v148 offset:2048
	ds_read_b128 v[246:249], v148 offset:3072
	global_load_lds_dwordx4 v[146:147], off
	v_lshl_add_u64 v[146:147], v[170:171], 0, s[34:35]
	s_add_i32 m0, s25, 0x2000
	s_nop 0
	global_load_lds_dwordx4 v[146:147], off
	s_barrier
	s_waitcnt lgkmcnt(0)
	s_waitcnt lgkmcnt(0)
	v_mfma_f32_16x16x32_bf16 v[124:127], v[234:237], v[190:193], v[124:127]
	v_mfma_f32_16x16x32_bf16 v[116:119], v[242:245], v[190:193], v[116:119]
	v_mfma_f32_16x16x32_bf16 v[108:111], v[234:237], v[198:201], v[108:111]
	v_mfma_f32_16x16x32_bf16 v[100:103], v[242:245], v[198:201], v[100:103]
	v_mfma_f32_16x16x32_bf16 v[92:95], v[234:237], v[218:221], v[92:95]
	v_mfma_f32_16x16x32_bf16 v[84:87], v[242:245], v[218:221], v[84:87]
	v_mfma_f32_16x16x32_bf16 v[76:79], v[234:237], v[226:229], v[76:79]
	v_mfma_f32_16x16x32_bf16 v[68:71], v[242:245], v[226:229], v[68:71]
	v_mfma_f32_16x16x32_bf16 v[124:127], v[238:241], v[194:197], v[124:127]
	v_mfma_f32_16x16x32_bf16 v[116:119], v[246:249], v[194:197], v[116:119]
	v_mfma_f32_16x16x32_bf16 v[108:111], v[238:241], v[214:217], v[108:111]
	v_mfma_f32_16x16x32_bf16 v[100:103], v[246:249], v[214:217], v[100:103]
	v_mfma_f32_16x16x32_bf16 v[92:95], v[238:241], v[222:225], v[92:95]
	v_mfma_f32_16x16x32_bf16 v[84:87], v[246:249], v[222:225], v[84:87]
	v_mfma_f32_16x16x32_bf16 v[76:79], v[238:241], v[230:233], v[76:79]
	v_mfma_f32_16x16x32_bf16 v[68:71], v[246:249], v[230:233], v[68:71]
	s_mov_b32 m0, s39
	v_lshl_add_u64 v[146:147], v[250:251], 0, s[34:35]
	s_barrier
; __device__ __forceinline__ unsigned pack2(float lo, float hi) { unsigned r; asm("v_cvt_pk_bf16_f32 %0, %1, %2" : "=v"(r) : "v"(lo), "v"(hi)); return r; }
; #define PG8_STAGE(bufoff, gbase, voff) do { _Pragma("unroll") for (int _i = 0; _i < 2; ++_i) \
;         __builtin_amdgcn_global_load_lds((const unsigned*)((const char*)(gbase) + (voff)[_i]), (LAS unsigned*)(lds + (bufoff) + ldsw + _i * 8192), 16, 0, 0); } while (0)
; #define PG8_MMA(ai, bj, At, Bt) do { __builtin_amdgcn_s_setprio(1); _Pragma("unroll") for (int m = 0; m < 4; ++m) _Pragma("unroll") for (int n = 0; n < 2; ++n) _Pragma("unroll") for (int k = 0; k < 2; ++k) \
;         acc[ai][bj][m][n] = __builtin_amdgcn_mfma_f32_16x16x32_bf16(Bt[n][k], At[m][k], acc[ai][bj][m][n], 0, 0, 0); __builtin_amdgcn_s_setprio(0); } while (0)
; #define PG8_WAIT_V(n) asm volatile("s_waitcnt vmcnt(" #n ")" ::: "memory")
; template <class Epi>
; __device__ __forceinline__ void gemm_phase(LAS unsigned char* lds, const Gemm g, const StaticOrder& S, const Epi& E) {
;     ...
;             PG8_BAR; PG8_WAIT_L(0); PG8_MMA(1, 0, At, B0); PG8_BAR; PG8_SCHED;
;             PG8_STAGE(PG8_SB(1, 1), b3 + hstep, voffB);
;             PG8_WAIT_V(6); PG8_BAR; PG8_MMA(1, 1, At, B1); PG8_BAR;
;     __device__ __forceinline__ void operator()(const AccT& acc, const pg8::Unit& u, int wr, int wc, int fr, int fq) const {
;         const int row0 = u.pm * 256 + wr * 64 + fr, col0 = u.pn * 256 + wc * 32 + 8 * fq;
;         const bool side_dt = (u.pn == 18 && wc == 0), side_if = (u.pn == 34 && wc == 1);
; #pragma unroll
;         for (int ai = 0; ai < 2; ++ai)
; #pragma unroll
;             for (int m = 0; m < 4; ++m) {
;                 const int row = row0 + ai * 128 + m * 16;
;                 bf16_t* rowp = U + (size_t)row * N1P + col0;
; #pragma unroll
;                 for (int bj = 0; bj < 2; ++bj) {
;                     const f32x4 v0 = acc[ai][bj][m][0], v1 = acc[ai][bj][m][1];
;                     u32x4 o; o[0] = pack2(v0[0], v0[1]); o[1] = pack2(v0[2], v0[3]); o[2] = pack2(v1[0], v1[1]); o[3] = pack2(v1[2], v1[3]);
;                     *(u32x4*)(rowp + bj * 128) = o;
;                 }
;                 if (side_dt || side_if) {
;                     float* sp = sf + (size_t)row * 64 + (side_if ? 32 : 0) + 8 * fq;
;                     *(f32x4*)sp = acc[ai][0][m][0]; *(f32x4*)(sp + 4) = acc[ai][0][m][1];
;                 }
	ds_read_b128 v[190:193], v172 offset:49152
	ds_read_b128 v[194:197], v172 offset:50176
	ds_read_b128 v[198:201], v172 offset:51200
	ds_read_b128 v[214:217], v172 offset:52224
	ds_read_b128 v[218:221], v172 offset:53248
	ds_read_b128 v[222:225], v172 offset:54272
	ds_read_b128 v[226:229], v172 offset:55296
	ds_read_b128 v[230:233], v172 offset:56320
	global_load_lds_dwordx4 v[146:147], off
	v_lshl_add_u64 v[146:147], v[252:253], 0, s[34:35]
	s_mov_b32 m0, s40
	s_nop 0
	global_load_lds_dwordx4 v[146:147], off
	s_barrier
	s_waitcnt lgkmcnt(0)
	s_waitcnt lgkmcnt(0)
	v_mfma_f32_16x16x32_bf16 v[64:67], v[174:177], v[190:193], v[64:67]
	v_mfma_f32_16x16x32_bf16 v[56:59], v[182:185], v[190:193], v[56:59]
	v_mfma_f32_16x16x32_bf16 v[48:51], v[174:177], v[198:201], v[48:51]
	v_mfma_f32_16x16x32_bf16 v[40:43], v[182:185], v[198:201], v[40:43]
	v_mfma_f32_16x16x32_bf16 v[32:35], v[174:177], v[218:221], v[32:35]
	v_mfma_f32_16x16x32_bf16 v[24:27], v[182:185], v[218:221], v[24:27]
	v_mfma_f32_16x16x32_bf16 v[16:19], v[174:177], v[226:229], v[16:19]
	v_mfma_f32_16x16x32_bf16 v[8:11], v[182:185], v[226:229], v[8:11]
	v_mfma_f32_16x16x32_bf16 v[64:67], v[178:181], v[194:197], v[64:67]
	v_mfma_f32_16x16x32_bf16 v[56:59], v[186:189], v[194:197], v[56:59]
	v_mfma_f32_16x16x32_bf16 v[48:51], v[178:181], v[214:217], v[48:51]
	v_mfma_f32_16x16x32_bf16 v[40:43], v[186:189], v[214:217], v[40:43]
	v_mfma_f32_16x16x32_bf16 v[32:35], v[178:181], v[222:225], v[32:35]
	v_mfma_f32_16x16x32_bf16 v[24:27], v[186:189], v[222:225], v[24:27]
	v_mfma_f32_16x16x32_bf16 v[16:19], v[178:181], v[230:233], v[16:19]
	v_mfma_f32_16x16x32_bf16 v[8:11], v[186:189], v[230:233], v[8:11]
	s_barrier
	s_add_u32 s22, s22, 0x80080
	s_addc_u32 s23, s23, 0
	s_add_i32 s24, s24, s30
	v_lshl_add_u64 v[146:147], s[22:23], 0, v[136:137]
	s_mov_b32 m0, s24
	s_nop 0
	global_load_lds_dwordx4 v[146:147], off
	v_lshl_add_u64 v[146:147], s[22:23], 0, v[132:133]
	s_add_i32 m0, s24, 0x2000
	s_nop 0
	global_load_lds_dwordx4 v[146:147], off
	s_waitcnt vmcnt(6)
	s_barrier
	v_mfma_f32_16x16x32_bf16 v[60:63], v[234:237], v[190:193], v[60:63]
	v_mfma_f32_16x16x32_bf16 v[52:55], v[242:245], v[190:193], v[52:55]
	v_mfma_f32_16x16x32_bf16 v[44:47], v[234:237], v[198:201], v[44:47]
	v_mfma_f32_16x16x32_bf16 v[36:39], v[242:245], v[198:201], v[36:39]
	v_mfma_f32_16x16x32_bf16 v[28:31], v[234:237], v[218:221], v[28:31]
	v_mfma_f32_16x16x32_bf16 v[20:23], v[242:245], v[218:221], v[20:23]
	v_mfma_f32_16x16x32_bf16 v[12:15], v[234:237], v[226:229], v[12:15]
	v_mfma_f32_16x16x32_bf16 v[4:7], v[242:245], v[226:229], v[4:7]
	v_mfma_f32_16x16x32_bf16 v[60:63], v[238:241], v[194:197], v[60:63]
	v_mfma_f32_16x16x32_bf16 v[52:55], v[246:249], v[194:197], v[52:55]
	v_mfma_f32_16x16x32_bf16 v[44:47], v[238:241], v[214:217], v[44:47]
	v_mfma_f32_16x16x32_bf16 v[36:39], v[246:249], v[214:217], v[36:39]
	v_mfma_f32_16x16x32_bf16 v[28:31], v[238:241], v[222:225], v[28:31]
	v_mfma_f32_16x16x32_bf16 v[20:23], v[246:249], v[222:225], v[20:23]
	v_mfma_f32_16x16x32_bf16 v[12:15], v[238:241], v[230:233], v[12:15]
	v_mfma_f32_16x16x32_bf16 v[4:7], v[246:249], v[230:233], v[4:7]
	s_add_i32 s47, s47, 2
	s_add_u32 s20, s20, 0x100
	s_addc_u32 s21, s21, 0
	s_add_u32 s44, s44, 0x100
	s_addc_u32 s46, s46, 0
	s_cmp_gt_u32 s47, 29
	s_barrier
	s_cbranch_scc0 .LBB0_758
	s_cmp_eq_u32 s5, 18
	s_cselect_b64 s[20:21], -1, 0
	s_and_b64 s[20:21], s[8:9], s[20:21]
	s_cmp_eq_u32 s5, 34
	v_lshl_add_u32 v170, s4, 8, v141
	v_lshl_or_b32 v146, s5, 8, v163
	s_cselect_b64 s[4:5], -1, 0
	s_and_b64 s[4:5], s[10:11], s[4:5]
	s_or_b64 s[20:21], s[20:21], s[4:5]
	v_mov_b64_e32 v[174:175], s[2:3]
	v_ashrrev_i32_e32 v147, 31, v146
	s_and_b64 s[4:5], s[4:5], exec
	v_mad_i64_i32 v[174:175], s[4:5], v170, s45, v[174:175]
	v_cvt_pk_bf16_f32 v124, v124, v125
	v_cvt_pk_bf16_f32 v125, v126, v127
	v_cvt_pk_bf16_f32 v126, v116, v117
	v_cndmask_b32_e64 v116, 0, 1, s[20:21]
	s_cselect_b32 s13, 32, 0
	v_ashrrev_i32_e32 v171, 31, v170
	v_lshl_add_u64 v[178:179], v[146:147], 1, v[174:175]
	v_cmp_ne_u32_e64 s[4:5], 1, v116
	s_andn2_b64 vcc, exec, s[20:21]
	v_lshlrev_b32_e32 v148, 2, v140
	v_cvt_pk_bf16_f32 v174, v128, v129
	v_cvt_pk_bf16_f32 v175, v130, v131
	v_cvt_pk_bf16_f32 v176, v120, v121
	v_cvt_pk_bf16_f32 v177, v122, v123
	global_store_dwordx4 v[178:179], v[174:177], off
	v_cvt_pk_bf16_f32 v127, v118, v119
	global_store_dwordx4 v[178:179], v[124:127], off offset:256
	s_cbranch_vccnz .LBB0_761
	v_lshlrev_b64 v[116:117], 8, v[170:171]
	v_lshl_add_u64 v[116:117], s[6:7], 0, v[116:117]
	s_lshl_b32 s96, s13, 2
	v_lshl_add_u64 v[116:117], v[116:117], 0, s[96:97]
	v_lshl_add_u64 v[116:117], v[116:117], 0, v[148:149]
	global_store_dwordx4 v[116:117], v[128:131], off
	global_store_dwordx4 v[116:117], v[120:123], off offset:16
